# C modes: near/far decision computed on SALU
# speedup vs baseline: 1.0083x; 1.0083x over previous
; #define SBAR() __builtin_amdgcn_sched_barrier(0)
; __device__ __forceinline__ void finishSM(f32x16& p0, f32x16& p1, float alpha, float& l_reg, bf16x8& pa0, bf16x8& pa1, bf16x8& pa2, bf16x8& pa3) {
; #pragma unroll
;   for (int r = 0; r < 16; ++r) p1[r] = __builtin_amdgcn_exp2f(p1[r]);
;   float ps = 0;
; #pragma unroll
;   for (int r = 0; r < 16; ++r) ps += p0[r];
; #pragma unroll
;   for (int r = 0; r < 16; ++r) ps += p1[r];
;   { auto rr = __builtin_amdgcn_permlane32_swap(__float_as_uint(ps), __float_as_uint(ps), false, false);
;     ps = __uint_as_float(rr[0]) + __uint_as_float(rr[1]); }
;   l_reg = l_reg * alpha + ps;
;     ...
;   PK4(p0, 0, pa0); PK4(p0, 8, pa1); PK4(p1, 0, pa2); PK4(p1, 8, pa3);
;     ...
; }
; template <int ND0, int DOFF>
; __device__ __forceinline__ void qkt(f32x16& p0, f32x16& p1, const char* Ks, const bf16x8* qr, int r32, int hi) {
;   p0 = f32x16{}; p1 = f32x16{};
; #pragma unroll
;   for (int d0 = 0; d0 < ND0; ++d0) { const int cb = ((d0 + DOFF) * 16 + hi * 8) * 2;
;     bf16x8 b0 = *reinterpret_cast<const bf16x8*>(Ks + KSWZ(r32, cb));
;     bf16x8 b1 = *reinterpret_cast<const bf16x8*>(Ks + KSWZ(32 + r32, cb));
;     p0 = __builtin_amdgcn_mfma_f32_32x32x16_bf16(b0, qr[d0], p0, 0, 0, 0);
;     p1 = __builtin_amdgcn_mfma_f32_32x32x16_bf16(b1, qr[d0], p1, 0, 0, 0); }
; }
; __device__ __forceinline__ int v_st(int k, int c) { const int kk = (k & ~0xC) | ((k & 4) << 1) | ((k & 8) >> 1); return ((kk >> 3) * 4 + (c >> 5)) * 512 + ((kk & 7) * 32 + (c & 31)) * 2; }
; __device__ __forceinline__ int v_rd_base(int lane) { return ((lane & 3) << 3) | (((lane >> 2) & 3) << 6) | (((lane >> 4) & 1) << 5) | (((lane >> 5) & 1) << 8); }
; template <int OFF> __device__ __forceinline__ s16x4 tr_read(int vb) {
;   s16x4 r; asm volatile("ds_read_b64_tr_b16 %0, %1 offset:%2" : "=&v"(r) : "v"(vb), "i"(OFF) : "memory"); return r;
; }
; template <int D0> __device__ __forceinline__ void pv_one(f32x16& od, int vb, bf16x8 pa0, bf16x8 pa1, bf16x8 pa2, bf16x8 pa3) {
;   const s16x4 l0 = tr_read<v_rd_off(D0, 0, 0)>(vb), h0 = tr_read<v_rd_off(D0, 0, 1)>(vb), l1 = tr_read<v_rd_off(D0, 1, 0)>(vb), h1 = tr_read<v_rd_off(D0, 1, 1)>(vb);
;   const s16x4 l2 = tr_read<v_rd_off(D0, 2, 0)>(vb), h2 = tr_read<v_rd_off(D0, 2, 1)>(vb), l3 = tr_read<v_rd_off(D0, 3, 0)>(vb), h3 = tr_read<v_rd_off(D0, 3, 1)>(vb);
;   asm volatile("s_waitcnt lgkmcnt(0)" ::: "memory"); SBAR();
.LBB0_132:
	v_readfirstlane_b32 s20, v221
	v_readfirstlane_b32 s21, v220
	s_nop 3
	s_add_i32 s22, s20, s77
	s_addk_i32 s22, 0x7f
	s_add_i32 s23, s21, s77
	s_addk_i32 s23, 0x40
	s_add_i32 s24, s22, 64
	s_add_i32 s25, s23, 64
	s_mov_b32 s79, s64
	s_waitcnt lgkmcnt(0)
	s_barrier
	s_add_i32 s64, s82, 0
	v_add_u32_e32 v0, s64, v213
	ds_read_b128 v[98:101], v0 offset:49152
	ds_read_b128 v[102:105], v0 offset:57344
	v_add_u32_e32 v0, s64, v214
	ds_read_b128 v[162:165], v0 offset:49152
	ds_read_b128 v[166:169], v0 offset:57344
	v_add_u32_e32 v0, s64, v215
	s_waitcnt lgkmcnt(3)
	v_mfma_f32_32x32x16_bf16 v[114:129], v[98:101], v[142:145], 0
	s_waitcnt lgkmcnt(2)
	v_mfma_f32_32x32x16_bf16 v[98:113], v[102:105], v[142:145], 0
	s_waitcnt lgkmcnt(1)
	v_mfma_f32_32x32x16_bf16 v[114:129], v[162:165], v[138:141], v[114:129]
	s_waitcnt lgkmcnt(0)
	v_mfma_f32_32x32x16_bf16 v[98:113], v[166:169], v[138:141], v[98:113]
	ds_read_b128 v[162:165], v0 offset:49152
	ds_read_b128 v[166:169], v0 offset:57344
	v_add_u32_e32 v0, s64, v216
	s_waitcnt lgkmcnt(1)
	v_mfma_f32_32x32x16_bf16 v[114:129], v[162:165], v[134:137], v[114:129]
	s_waitcnt lgkmcnt(0)
	v_mfma_f32_32x32x16_bf16 v[98:113], v[166:169], v[134:137], v[98:113]
	ds_read_b128 v[162:165], v0 offset:49152
	ds_read_b128 v[166:169], v0 offset:57344
	v_exp_f32_e32 v0, v82
	v_exp_f32_e32 v82, v83
	v_exp_f32_e32 v83, v84
	v_exp_f32_e32 v84, v85
	v_exp_f32_e32 v85, v86
	v_exp_f32_e32 v86, v87
	v_exp_f32_e32 v87, v88
	v_exp_f32_e32 v88, v89
	v_exp_f32_e32 v89, v90
	v_exp_f32_e32 v90, v91
	v_exp_f32_e32 v91, v92
	v_exp_f32_e32 v92, v93
	v_exp_f32_e32 v93, v94
	v_exp_f32_e32 v94, v95
	v_exp_f32_e32 v95, v96
	v_exp_f32_e32 v96, v97
	v_add_f32_e32 v97, v67, v66
	v_add_f32_e32 v97, v68, v97
	v_add_f32_e32 v97, v69, v97
	v_add_f32_e32 v97, v70, v97
	v_add_f32_e32 v97, v71, v97
	v_add_f32_e32 v97, v72, v97
	v_add_f32_e32 v97, v73, v97
	v_add_f32_e32 v97, v74, v97
	v_add_f32_e32 v97, v75, v97
	v_add_f32_e32 v97, v76, v97
	v_add_f32_e32 v97, v77, v97
	v_add_f32_e32 v97, v78, v97
	v_add_f32_e32 v97, v79, v97
	v_add_f32_e32 v97, v80, v97
	v_add_f32_e32 v97, v81, v97
	v_add_f32_e32 v97, v0, v97
	v_add_f32_e32 v97, v82, v97
	v_add_f32_e32 v97, v83, v97
	v_add_f32_e32 v97, v84, v97
	v_add_f32_e32 v97, v85, v97
	v_add_f32_e32 v97, v86, v97
	v_add_f32_e32 v97, v87, v97
	v_add_f32_e32 v97, v88, v97
	v_add_f32_e32 v97, v89, v97
	v_add_f32_e32 v97, v90, v97
	s_waitcnt lgkmcnt(1)
	v_mfma_f32_32x32x16_bf16 v[114:129], v[162:165], v[130:133], v[114:129]
	v_add_f32_e32 v97, v91, v97
	v_add_f32_e32 v97, v92, v97
	v_add_f32_e32 v97, v93, v97
	v_add_f32_e32 v97, v94, v97
	v_add_f32_e32 v97, v95, v97
	v_add_f32_e32 v223, v96, v97
	v_mov_b32_e32 v224, v223
	s_waitcnt lgkmcnt(0)
	v_mfma_f32_32x32x16_bf16 v[98:113], v[166:169], v[130:133], v[98:113]
	v_cvt_pk_bf16_f32 v66, v66, v67
	v_cvt_pk_bf16_f32 v67, v68, v69
	v_cvt_pk_bf16_f32 v68, v70, v71
	v_cvt_pk_bf16_f32 v69, v72, v73
	v_cvt_pk_bf16_f32 v70, v74, v75
	v_cvt_pk_bf16_f32 v71, v76, v77
	v_cvt_pk_bf16_f32 v72, v78, v79
	v_cvt_pk_bf16_f32 v73, v80, v81
	v_cvt_pk_bf16_f32 v74, v0, v82
	v_cvt_pk_bf16_f32 v75, v83, v84
	v_cvt_pk_bf16_f32 v76, v85, v86
	v_cvt_pk_bf16_f32 v77, v87, v88
	v_cvt_pk_bf16_f32 v78, v89, v90
	v_cvt_pk_bf16_f32 v79, v91, v92
	v_cvt_pk_bf16_f32 v80, v93, v94
	v_cvt_pk_bf16_f32 v81, v95, v96
	v_permlane32_swap_b32_e32 v223, v224
	v_permlane32_swap_b32_e32 v66, v68
	v_permlane32_swap_b32_e32 v67, v69
	v_permlane32_swap_b32_e32 v70, v72
	v_permlane32_swap_b32_e32 v71, v73
	v_permlane32_swap_b32_e32 v74, v76
	v_permlane32_swap_b32_e32 v75, v77
	v_permlane32_swap_b32_e32 v78, v80
	v_permlane32_swap_b32_e32 v79, v81
	v_add_co_u32_e32 v82, vcc, s4, v190
	s_nop 1
	v_addc_co_u32_e32 v83, vcc, -1, v191, vcc
	v_add_co_u32_e32 v84, vcc, s5, v190
	s_nop 1
	v_addc_co_u32_e32 v85, vcc, -1, v191, vcc
	global_load_dwordx4 v[162:165], v[82:83], off
	global_load_dwordx4 v[166:169], v[82:83], off offset:-512
	global_load_dwordx4 v[174:177], v[84:85], off
	global_load_dwordx4 v[170:173], v[84:85], off offset:-512
	v_add_u32_e32 v0, s80, v218
	ds_read_b64_tr_b16 v[82:83], v0 offset:0
	ds_read_b64_tr_b16 v[84:85], v0 offset:0x800
	ds_read_b64_tr_b16 v[86:87], v0 offset:0x1000
	ds_read_b64_tr_b16 v[88:89], v0 offset:0x1800
	ds_read_b64_tr_b16 v[90:91], v0 offset:0x2000
	ds_read_b64_tr_b16 v[92:93], v0 offset:0x2800
	ds_read_b64_tr_b16 v[94:95], v0 offset:0x3000
	ds_read_b64_tr_b16 v[96:97], v0 offset:0x3800
	s_waitcnt lgkmcnt(0)
	s_nop 0
	v_mfma_f32_32x32x16_bf16 v[50:65], v[66:69], v[82:85], v[50:65]
	ds_read_b64_tr_b16 v[82:83], v0 offset:0x200
	ds_read_b64_tr_b16 v[84:85], v0 offset:0xa00
	v_mfma_f32_32x32x16_bf16 v[50:65], v[70:73], v[86:89], v[50:65]
	ds_read_b64_tr_b16 v[86:87], v0 offset:0x1200
	ds_read_b64_tr_b16 v[88:89], v0 offset:0x1a00
	v_mfma_f32_32x32x16_bf16 v[50:65], v[74:77], v[90:93], v[50:65]
	ds_read_b64_tr_b16 v[90:91], v0 offset:0x2200
	ds_read_b64_tr_b16 v[92:93], v0 offset:0x2a00
	v_mfma_f32_32x32x16_bf16 v[50:65], v[78:81], v[94:97], v[50:65]
	ds_read_b64_tr_b16 v[94:95], v0 offset:0x3200
	ds_read_b64_tr_b16 v[96:97], v0 offset:0x3a00
	s_waitcnt lgkmcnt(0)
	v_mfma_f32_32x32x16_bf16 v[34:49], v[66:69], v[82:85], v[34:49]
	ds_read_b64_tr_b16 v[82:83], v0 offset:0x400
	ds_read_b64_tr_b16 v[84:85], v0 offset:0xc00
	v_mfma_f32_32x32x16_bf16 v[34:49], v[70:73], v[86:89], v[34:49]
	ds_read_b64_tr_b16 v[86:87], v0 offset:0x1400
	ds_read_b64_tr_b16 v[88:89], v0 offset:0x1c00
	v_mfma_f32_32x32x16_bf16 v[34:49], v[74:77], v[90:93], v[34:49]
	ds_read_b64_tr_b16 v[90:91], v0 offset:0x2400
	ds_read_b64_tr_b16 v[92:93], v0 offset:0x2c00
	v_mfma_f32_32x32x16_bf16 v[34:49], v[78:81], v[94:97], v[34:49]
	ds_read_b64_tr_b16 v[94:95], v0 offset:0x3400
	ds_read_b64_tr_b16 v[96:97], v0 offset:0x3c00
	s_waitcnt lgkmcnt(0)
	v_mfma_f32_32x32x16_bf16 v[18:33], v[66:69], v[82:85], v[18:33]
	ds_read_b64_tr_b16 v[82:83], v0 offset:0x600
	ds_read_b64_tr_b16 v[84:85], v0 offset:0xe00
	v_mfma_f32_32x32x16_bf16 v[18:33], v[70:73], v[86:89], v[18:33]
	ds_read_b64_tr_b16 v[86:87], v0 offset:0x1600
	ds_read_b64_tr_b16 v[88:89], v0 offset:0x1e00
	v_mfma_f32_32x32x16_bf16 v[18:33], v[74:77], v[90:93], v[18:33]
	ds_read_b64_tr_b16 v[90:91], v0 offset:0x2600
	ds_read_b64_tr_b16 v[92:93], v0 offset:0x2e00
	v_mfma_f32_32x32x16_bf16 v[18:33], v[78:81], v[94:97], v[18:33]
	ds_read_b64_tr_b16 v[94:95], v0 offset:0x3600
	ds_read_b64_tr_b16 v[96:97], v0 offset:0x3e00
	s_waitcnt lgkmcnt(0)
	v_mfma_f32_32x32x16_bf16 v[2:17], v[66:69], v[82:85], v[2:17]
	s_cmp_gt_i32 s95, s22
	s_cselect_b64 s[64:65], -1, 0
	s_cmp_lt_i32 s15, s22
	s_cselect_b64 vcc, -1, 0
	v_mov_b32_e32 v229, s76
	v_mfma_f32_32x32x16_bf16 v[2:17], v[70:73], v[86:89], v[2:17]
	v_mfma_f32_32x32x16_bf16 v[2:17], v[74:77], v[90:93], v[2:17]
	v_mfma_f32_32x32x16_bf16 v[2:17], v[78:81], v[94:97], v[2:17]
	s_and_saveexec_b64 s[66:67], vcc
	s_cbranch_execz .LBB0_136
; template <int MODE>
; __device__ __forceinline__ void partialSM(f32x16& p0, f32x16& p1, float& m_reg, float& mn, float& alpha, int relh, int relw_min, int relw_max, const float* lut) {
;     ...
;       if (relw_max <= -128) { nearT = false; cfar = lut[0]; }
;       else if (relw_min >= 128) { nearT = false; cfar = lut[258]; }
;       if (!nearT) {
;         float pmax = p0[0];
; #pragma unroll
;         for (int r = 1; r < 16; ++r) pmax = fmaxf(pmax, p0[r]);
; #pragma unroll
;         for (int r = 0; r < 16; ++r) pmax = fmaxf(pmax, p1[r]);
;         { auto rr = __builtin_amdgcn_permlane32_swap(__float_as_uint(pmax), __float_as_uint(pmax), false, false);
;           pmax = fmaxf(__uint_as_float(rr[0]), __uint_as_float(rr[1])); }
;         const float tmax = fmaf(pmax, C, cfar);
;         if (__builtin_expect(__all(tmax - m_reg <= THR2), 1)) { mn = m_reg; alpha = 1.f; }
;         else { mn = fmaxf(m_reg, tmax); alpha = __builtin_amdgcn_exp2f(m_reg - mn); m_reg = mn; }
;         const float off = cfar - mn;
; #pragma unroll
;         for (int r = 0; r < 16; ++r) p0[r] = fmaf(p0[r], C, off);
; #pragma unroll
;         for (int r = 0; r < 16; ++r) p1[r] = fmaf(p1[r], C, off);
; #pragma unroll
;         for (int r = 0; r < 16; ++r) p0[r] = __builtin_amdgcn_exp2f(p0[r]);
;         return;
;       }
;     }
;     if (nearT) {
; #pragma unroll
;       for (int r = 0; r < 16; ++r) { const int i0 = relh + (r & 3) + 8 * (r >> 2);
;         const int a0 = min(max(i0, -129), 129) + 129, a1 = min(max(i0 + 32, -129), 129) + 129;
;         p0[r] = fmaf(p0[r], C, lut[a0]); p1[r] = fmaf(p1[r], C, lut[a1]); }
	s_cmp_gt_i32 s91, s23
	s_cselect_b64 vcc, -1, 0
	s_mov_b64 s[70:71], -1
	s_and_saveexec_b64 s[68:69], vcc
	s_cbranch_execz .LBB0_135
	v_add_u32_e32 v227, s77, v222
	v_add_u32_e32 v66, 64, v227
	v_add_u32_e32 v68, 0x41, v227
	v_add_u32_e32 v70, 0x42, v227
	v_add_u32_e32 v72, 0x43, v227
	v_med3_i32 v67, v66, s39, v198
	v_med3_i32 v66, v66, s33, v199
	v_med3_i32 v69, v68, s39, v198
	v_med3_i32 v68, v68, s33, v199
	v_med3_i32 v71, v70, s39, v198
	v_med3_i32 v70, v70, s33, v199
	v_med3_i32 v73, v72, s39, v198
	v_med3_i32 v72, v72, s33, v199
	v_lshl_add_u32 v67, v67, 2, s76
	v_lshl_add_u32 v66, v66, 2, s76
	v_lshl_add_u32 v69, v69, 2, s76
	v_lshl_add_u32 v68, v68, 2, s76
	v_lshl_add_u32 v70, v70, 2, s76
	v_lshl_add_u32 v72, v72, 2, s76
	v_lshl_add_u32 v71, v71, 2, s76
	v_lshl_add_u32 v73, v73, 2, s76
	ds_read_b32 v194, v67 offset:516
	ds_read_b32 v66, v66 offset:644
	ds_read_b32 v195, v69 offset:516
	ds_read_b32 v67, v68 offset:644
	ds_read_b32 v229, v71 offset:516
	ds_read_b32 v68, v70 offset:644
	ds_read_b32 v230, v73 offset:516
	ds_read_b32 v69, v72 offset:644
	v_add_u32_e32 v70, 0x48, v227
	v_add_u32_e32 v72, 0x49, v227
	v_add_u32_e32 v74, 0x4a, v227
	v_add_u32_e32 v76, 0x4b, v227
	v_med3_i32 v71, v70, s39, v198
	v_med3_i32 v70, v70, s33, v199
	v_med3_i32 v73, v72, s39, v198
	v_med3_i32 v72, v72, s33, v199
	v_med3_i32 v75, v74, s39, v198
	v_med3_i32 v74, v74, s33, v199
	v_med3_i32 v77, v76, s39, v198
	v_med3_i32 v76, v76, s33, v199
	v_lshl_add_u32 v71, v71, 2, s76
	v_lshl_add_u32 v70, v70, 2, s76
	v_lshl_add_u32 v73, v73, 2, s76
	v_lshl_add_u32 v72, v72, 2, s76
	v_lshl_add_u32 v74, v74, 2, s76
	v_lshl_add_u32 v76, v76, 2, s76
	v_lshl_add_u32 v75, v75, 2, s76
	v_lshl_add_u32 v77, v77, 2, s76
	ds_read_b32 v231, v71 offset:516
	ds_read_b32 v70, v70 offset:644
	ds_read_b32 v232, v73 offset:516
	ds_read_b32 v71, v72 offset:644
	ds_read_b32 v233, v75 offset:516
	ds_read_b32 v72, v74 offset:644
	ds_read_b32 v234, v77 offset:516
	ds_read_b32 v73, v76 offset:644
	v_add_u32_e32 v74, 0x50, v227
	v_add_u32_e32 v76, 0x51, v227
	v_add_u32_e32 v78, 0x52, v227
	v_add_u32_e32 v80, 0x53, v227
	v_med3_i32 v75, v74, s39, v198
	v_med3_i32 v74, v74, s33, v199
	v_med3_i32 v77, v76, s39, v198
	v_med3_i32 v76, v76, s33, v199
	v_med3_i32 v79, v78, s39, v198
	v_med3_i32 v78, v78, s33, v199
	v_med3_i32 v81, v80, s39, v198
	v_med3_i32 v80, v80, s33, v199
	v_lshl_add_u32 v75, v75, 2, s76
	v_lshl_add_u32 v74, v74, 2, s76
	v_lshl_add_u32 v77, v77, 2, s76
	v_lshl_add_u32 v76, v76, 2, s76
	v_lshl_add_u32 v78, v78, 2, s76
	v_lshl_add_u32 v80, v80, 2, s76
	v_lshl_add_u32 v79, v79, 2, s76
	v_lshl_add_u32 v81, v81, 2, s76
	ds_read_b32 v235, v75 offset:516
	ds_read_b32 v74, v74 offset:644
	ds_read_b32 v236, v77 offset:516
	ds_read_b32 v75, v76 offset:644
	ds_read_b32 v237, v79 offset:516
	ds_read_b32 v76, v78 offset:644
	ds_read_b32 v238, v81 offset:516
	ds_read_b32 v77, v80 offset:644
	v_add_u32_e32 v78, 0x58, v227
	v_add_u32_e32 v80, 0x59, v227
	v_add_u32_e32 v82, 0x5a, v227
	v_med3_i32 v79, v78, s39, v198
	v_med3_i32 v78, v78, s33, v199
	v_med3_i32 v81, v80, s39, v198
	v_med3_i32 v80, v80, s33, v199
	v_med3_i32 v83, v82, s39, v198
	v_med3_i32 v82, v82, s33, v199
	v_add_u32_e32 v84, 0x5b, v227
	s_waitcnt lgkmcnt(14)
	v_fmac_f32_e32 v194, 0x3e38aa3b, v114
	v_fmac_f32_e32 v195, 0x3e38aa3b, v115
	v_lshl_add_u32 v79, v79, 2, s76
	v_lshl_add_u32 v78, v78, 2, s76
	v_lshl_add_u32 v81, v81, 2, s76
	v_lshl_add_u32 v80, v80, 2, s76
	v_lshl_add_u32 v82, v82, 2, s76
	v_med3_i32 v85, v84, s39, v198
	v_med3_i32 v84, v84, s33, v199
	v_fmac_f32_e32 v229, 0x3e38aa3b, v116
	v_fmac_f32_e32 v230, 0x3e38aa3b, v117
	v_lshl_add_u32 v83, v83, 2, s76
	v_lshl_add_u32 v85, v85, 2, s76
	v_lshl_add_u32 v84, v84, 2, s76
	ds_read_b32 v239, v79 offset:516
	ds_read_b32 v78, v78 offset:644
	ds_read_b32 v240, v81 offset:516
	ds_read_b32 v79, v80 offset:644
	ds_read_b32 v241, v83 offset:516
	ds_read_b32 v80, v82 offset:644
	ds_read_b32 v242, v85 offset:516
	ds_read_b32 v81, v84 offset:644
	v_max_f32_e32 v82, v194, v195
	v_fmac_f32_e32 v231, 0x3e38aa3b, v118
	s_waitcnt lgkmcnt(14)
; template <int MODE>
; __device__ __forceinline__ void partialSM(f32x16& p0, f32x16& p1, float& m_reg, float& mn, float& alpha, int relh, int relw_min, int relw_max, const float* lut) {
;     ...
;     if (nearT) {
; #pragma unroll
;       for (int r = 0; r < 16; ++r) { const int i0 = relh + (r & 3) + 8 * (r >> 2);
;         const int a0 = min(max(i0, -129), 129) + 129, a1 = min(max(i0 + 32, -129), 129) + 129;
;         p0[r] = fmaf(p0[r], C, lut[a0]); p1[r] = fmaf(p1[r], C, lut[a1]); }
;     } else {
; #pragma unroll
;       for (int r = 0; r < 16; ++r) { p0[r] = fmaf(p0[r], C, cfar); p1[r] = fmaf(p1[r], C, cfar); }
;     }
;     float pmax = p0[0];
; #pragma unroll
;     for (int r = 1; r < 16; ++r) pmax = fmaxf(pmax, p0[r]);
; #pragma unroll
;     for (int r = 0; r < 16; ++r) pmax = fmaxf(pmax, p1[r]);
;     { auto rr = __builtin_amdgcn_permlane32_swap(__float_as_uint(pmax), __float_as_uint(pmax), false, false);
;       pmax = fmaxf(__uint_as_float(rr[0]), __uint_as_float(rr[1])); }
;     if (__builtin_expect(__all(pmax - m_reg <= THR2), 1)) { mn = m_reg; alpha = 1.f; }
;     else { mn = fmaxf(m_reg, pmax); alpha = __builtin_amdgcn_exp2f(m_reg - mn); m_reg = mn; }
; #pragma unroll
;     for (int r = 0; r < 16; ++r) p0[r] = __builtin_amdgcn_exp2f(p0[r] - mn);
; #pragma unroll
;     for (int r = 0; r < 16; ++r) p1[r] = p1[r] - mn;
	v_fmac_f32_e32 v232, 0x3e38aa3b, v119
	v_max3_f32 v82, v82, v229, v230
	v_fmac_f32_e32 v233, 0x3e38aa3b, v120
	v_fmac_f32_e32 v234, 0x3e38aa3b, v121
	v_max3_f32 v82, v82, v231, v232
	v_fmac_f32_e32 v235, 0x3e38aa3b, v122
	s_waitcnt lgkmcnt(13)
	v_fmac_f32_e32 v236, 0x3e38aa3b, v123
	v_max3_f32 v82, v82, v233, v234
	s_waitcnt lgkmcnt(11)
	v_fmac_f32_e32 v237, 0x3e38aa3b, v124
	s_waitcnt lgkmcnt(9)
	v_fmac_f32_e32 v238, 0x3e38aa3b, v125
	v_max3_f32 v82, v82, v235, v236
	s_waitcnt lgkmcnt(7)
	v_fmac_f32_e32 v239, 0x3e38aa3b, v126
	s_waitcnt lgkmcnt(5)
	v_fmac_f32_e32 v240, 0x3e38aa3b, v127
	v_max3_f32 v82, v82, v237, v238
	s_waitcnt lgkmcnt(3)
	v_fmac_f32_e32 v241, 0x3e38aa3b, v128
	s_waitcnt lgkmcnt(1)
	v_fmac_f32_e32 v242, 0x3e38aa3b, v129
	v_max3_f32 v82, v82, v239, v240
	v_max3_f32 v84, v82, v241, v242
	v_pk_fma_f32 v[82:83], v[98:99], s[48:49], v[66:67] op_sel_hi:[1,0,1]
	v_pk_fma_f32 v[86:87], v[102:103], s[48:49], v[70:71] op_sel_hi:[1,0,1]
	v_max3_f32 v66, v84, v82, v83
	v_pk_fma_f32 v[84:85], v[100:101], s[48:49], v[68:69] op_sel_hi:[1,0,1]
	v_pk_fma_f32 v[88:89], v[104:105], s[48:49], v[72:73] op_sel_hi:[1,0,1]
	v_max3_f32 v66, v66, v84, v85
	v_max3_f32 v66, v66, v86, v87
	v_max3_f32 v66, v66, v88, v89
	v_pk_fma_f32 v[90:91], v[106:107], s[48:49], v[74:75] op_sel_hi:[1,0,1]
	v_pk_fma_f32 v[92:93], v[108:109], s[48:49], v[76:77] op_sel_hi:[1,0,1]
	v_max3_f32 v66, v66, v90, v91
	v_max3_f32 v66, v66, v92, v93
	v_pk_fma_f32 v[94:95], v[110:111], s[48:49], v[78:79] op_sel_hi:[1,0,1]
	s_waitcnt lgkmcnt(0)
	v_pk_fma_f32 v[96:97], v[112:113], s[48:49], v[80:81] op_sel_hi:[1,0,1]
	v_max3_f32 v66, v66, v94, v95
	v_max3_f32 v66, v66, v96, v97
	v_mov_b32_e32 v67, v66
	s_nop 1
	v_permlane32_swap_b32_e32 v66, v67
	v_max_f32_e32 v66, v66, v67
	v_sub_f32_e32 v67, v66, v219
	v_cmp_ge_f32_e32 vcc, s94, v67
	v_max_f32_e32 v66, v219, v66
	v_sub_f32_e32 v67, v219, v66
	v_exp_f32_e32 v67, v67
	s_cmp_eq_u64 vcc, exec
	s_cselect_b64 vcc, -1, 0
	v_cndmask_b32_e32 v228, v66, v219, vcc
	v_cndmask_b32_e64 v226, v67, 1.0, vcc
	v_sub_f32_e32 v66, v194, v228
	v_sub_f32_e32 v67, v195, v228
	v_sub_f32_e32 v68, v229, v228
	v_sub_f32_e32 v69, v230, v228
	v_sub_f32_e32 v70, v231, v228
	v_sub_f32_e32 v71, v232, v228
	v_sub_f32_e32 v72, v233, v228
	v_sub_f32_e32 v73, v234, v228
	v_sub_f32_e32 v74, v235, v228
	v_sub_f32_e32 v75, v236, v228
	v_sub_f32_e32 v76, v237, v228
	v_sub_f32_e32 v77, v238, v228
	v_sub_f32_e32 v78, v239, v228
	v_sub_f32_e32 v79, v240, v228
	v_sub_f32_e32 v80, v241, v228
	v_sub_f32_e32 v81, v242, v228
	v_exp_f32_e32 v66, v66
	v_exp_f32_e32 v67, v67
	v_exp_f32_e32 v68, v68
	v_exp_f32_e32 v69, v69
	v_exp_f32_e32 v70, v70
	v_exp_f32_e32 v71, v71
	v_exp_f32_e32 v72, v72
	v_exp_f32_e32 v73, v73
	v_exp_f32_e32 v74, v74
	v_exp_f32_e32 v75, v75
	v_exp_f32_e32 v76, v76
	v_exp_f32_e32 v77, v77
	v_exp_f32_e32 v78, v78
	v_exp_f32_e32 v79, v79
	v_exp_f32_e32 v80, v80
	v_exp_f32_e32 v81, v81
	v_sub_f32_e32 v97, v97, v228
	v_sub_f32_e32 v96, v96, v228
	v_sub_f32_e32 v95, v95, v228
	v_sub_f32_e32 v94, v94, v228
	v_sub_f32_e32 v93, v93, v228
	v_sub_f32_e32 v92, v92, v228
	v_sub_f32_e32 v91, v91, v228
	v_sub_f32_e32 v90, v90, v228
	v_sub_f32_e32 v89, v89, v228
	v_sub_f32_e32 v88, v88, v228
	v_sub_f32_e32 v87, v87, v228
	v_sub_f32_e32 v86, v86, v228
	v_sub_f32_e32 v85, v85, v228
	v_sub_f32_e32 v84, v84, v228
	v_sub_f32_e32 v83, v83, v228
	v_sub_f32_e32 v82, v82, v228
	s_xor_b64 s[70:71], exec, -1

; template <int MODE>
; __device__ __forceinline__ void partialSM(f32x16& p0, f32x16& p1, float& m_reg, float& mn, float& alpha, int relh, int relw_min, int relw_max, const float* lut) {
;     ...
;       if (relw_max <= -128) { nearT = false; cfar = lut[0]; }
;       else if (relw_min >= 128) { nearT = false; cfar = lut[258]; }
;       if (!nearT) {
;         float pmax = p0[0];
; #pragma unroll
;         for (int r = 1; r < 16; ++r) pmax = fmaxf(pmax, p0[r]);
; #pragma unroll
;         for (int r = 0; r < 16; ++r) pmax = fmaxf(pmax, p1[r]);
;         { auto rr = __builtin_amdgcn_permlane32_swap(__float_as_uint(pmax), __float_as_uint(pmax), false, false);
;           pmax = fmaxf(__uint_as_float(rr[0]), __uint_as_float(rr[1])); }
;         const float tmax = fmaf(pmax, C, cfar);
;         if (__builtin_expect(__all(tmax - m_reg <= THR2), 1)) { mn = m_reg; alpha = 1.f; }
;         else { mn = fmaxf(m_reg, tmax); alpha = __builtin_amdgcn_exp2f(m_reg - mn); m_reg = mn; }
;         const float off = cfar - mn;
; #pragma unroll
; template <int OFF> __device__ __forceinline__ s16x4 tr_read(int vb) {
;   s16x4 r; asm volatile("ds_read_b64_tr_b16 %0, %1 offset:%2" : "=&v"(r) : "v"(vb), "i"(OFF) : "memory"); return r;
; }
; template <int D0> __device__ __forceinline__ void pv_one(f32x16& od, int vb, bf16x8 pa0, bf16x8 pa1, bf16x8 pa2, bf16x8 pa3) {
;   const s16x4 l0 = tr_read<v_rd_off(D0, 0, 0)>(vb), h0 = tr_read<v_rd_off(D0, 0, 1)>(vb), l1 = tr_read<v_rd_off(D0, 1, 0)>(vb), h1 = tr_read<v_rd_off(D0, 1, 1)>(vb);
;   const s16x4 l2 = tr_read<v_rd_off(D0, 2, 0)>(vb), h2 = tr_read<v_rd_off(D0, 2, 1)>(vb), l3 = tr_read<v_rd_off(D0, 3, 0)>(vb), h3 = tr_read<v_rd_off(D0, 3, 1)>(vb);
;   asm volatile("s_waitcnt lgkmcnt(0)" ::: "memory"); SBAR();
;     ...
;   od = __builtin_amdgcn_mfma_f32_32x32x16_bf16(pa0, PK(l0, h0), od, 0, 0, 0);
;   od = __builtin_amdgcn_mfma_f32_32x32x16_bf16(pa1, PK(l1, h1), od, 0, 0, 0);
;   od = __builtin_amdgcn_mfma_f32_32x32x16_bf16(pa2, PK(l2, h2), od, 0, 0, 0);
;   od = __builtin_amdgcn_mfma_f32_32x32x16_bf16(pa3, PK(l3, h3), od, 0, 0, 0);
;     ...
; }
; __device__ __forceinline__ void pv_d0(f32x16* o, int vb, bf16x8 pa0, bf16x8 pa1, bf16x8 pa2, bf16x8 pa3) {
;   pv_one<0>(o[0], vb, pa0, pa1, pa2, pa3); pv_one<1>(o[1], vb, pa0, pa1, pa2, pa3); pv_one<2>(o[2], vb, pa0, pa1, pa2, pa3); pv_one<3>(o[3], vb, pa0, pa1, pa2, pa3);
.LBB0_144:
	v_add_u32_e32 v194, s82, v218
	ds_read_b64_tr_b16 v[82:83], v194 offset:0
	ds_read_b64_tr_b16 v[84:85], v194 offset:0x800
	ds_read_b64_tr_b16 v[86:87], v194 offset:0x1000
	ds_read_b64_tr_b16 v[88:89], v194 offset:0x1800
	ds_read_b64_tr_b16 v[90:91], v194 offset:0x2000
	ds_read_b64_tr_b16 v[92:93], v194 offset:0x2800
	ds_read_b64_tr_b16 v[94:95], v194 offset:0x3000
	ds_read_b64_tr_b16 v[96:97], v194 offset:0x3800
	s_waitcnt lgkmcnt(0)
	s_nop 0
	v_mfma_f32_32x32x16_bf16 v[50:65], v[66:69], v[82:85], v[50:65]
	ds_read_b64_tr_b16 v[82:83], v194 offset:0x200
	ds_read_b64_tr_b16 v[84:85], v194 offset:0xa00
	v_mfma_f32_32x32x16_bf16 v[50:65], v[70:73], v[86:89], v[50:65]
	ds_read_b64_tr_b16 v[86:87], v194 offset:0x1200
	ds_read_b64_tr_b16 v[88:89], v194 offset:0x1a00
	v_mfma_f32_32x32x16_bf16 v[50:65], v[74:77], v[90:93], v[50:65]
	ds_read_b64_tr_b16 v[90:91], v194 offset:0x2200
	ds_read_b64_tr_b16 v[92:93], v194 offset:0x2a00
	v_mfma_f32_32x32x16_bf16 v[50:65], v[78:81], v[94:97], v[50:65]
	ds_read_b64_tr_b16 v[94:95], v194 offset:0x3200
	ds_read_b64_tr_b16 v[96:97], v194 offset:0x3a00
	s_waitcnt lgkmcnt(0)
	v_mfma_f32_32x32x16_bf16 v[34:49], v[66:69], v[82:85], v[34:49]
	ds_read_b64_tr_b16 v[82:83], v194 offset:0x400
	ds_read_b64_tr_b16 v[84:85], v194 offset:0xc00
	v_mfma_f32_32x32x16_bf16 v[34:49], v[70:73], v[86:89], v[34:49]
	ds_read_b64_tr_b16 v[86:87], v194 offset:0x1400
	ds_read_b64_tr_b16 v[88:89], v194 offset:0x1c00
	v_mfma_f32_32x32x16_bf16 v[34:49], v[74:77], v[90:93], v[34:49]
	ds_read_b64_tr_b16 v[90:91], v194 offset:0x2400
	ds_read_b64_tr_b16 v[92:93], v194 offset:0x2c00
	v_mfma_f32_32x32x16_bf16 v[34:49], v[78:81], v[94:97], v[34:49]
	ds_read_b64_tr_b16 v[94:95], v194 offset:0x3400
	ds_read_b64_tr_b16 v[96:97], v194 offset:0x3c00
	s_waitcnt lgkmcnt(0)
	v_mfma_f32_32x32x16_bf16 v[18:33], v[66:69], v[82:85], v[18:33]
	ds_read_b64_tr_b16 v[82:83], v194 offset:0x600
	ds_read_b64_tr_b16 v[84:85], v194 offset:0xe00
	v_mfma_f32_32x32x16_bf16 v[18:33], v[70:73], v[86:89], v[18:33]
	ds_read_b64_tr_b16 v[86:87], v194 offset:0x1600
	ds_read_b64_tr_b16 v[88:89], v194 offset:0x1e00
	v_mfma_f32_32x32x16_bf16 v[18:33], v[74:77], v[90:93], v[18:33]
	ds_read_b64_tr_b16 v[90:91], v194 offset:0x2600
	ds_read_b64_tr_b16 v[92:93], v194 offset:0x2e00
	v_mfma_f32_32x32x16_bf16 v[18:33], v[78:81], v[94:97], v[18:33]
	ds_read_b64_tr_b16 v[94:95], v194 offset:0x3600
	ds_read_b64_tr_b16 v[96:97], v194 offset:0x3e00
	s_waitcnt lgkmcnt(0)
	v_mfma_f32_32x32x16_bf16 v[2:17], v[66:69], v[82:85], v[2:17]
	s_cmp_gt_i32 s95, s24
	s_cselect_b64 s[66:67], -1, 0
	s_cmp_lt_i32 s15, s24
	s_cselect_b64 vcc, -1, 0
	v_mov_b32_e32 v231, s76
	v_mfma_f32_32x32x16_bf16 v[2:17], v[70:73], v[86:89], v[2:17]
	v_mfma_f32_32x32x16_bf16 v[2:17], v[74:77], v[90:93], v[2:17]
	v_mfma_f32_32x32x16_bf16 v[2:17], v[78:81], v[94:97], v[2:17]
	s_and_saveexec_b64 s[68:69], vcc
	s_cbranch_execz .LBB0_148
	s_cmp_gt_i32 s91, s25
	s_cselect_b64 vcc, -1, 0
	s_mov_b64 s[72:73], -1
	s_and_saveexec_b64 s[70:71], vcc
	s_cbranch_execz .LBB0_147
	v_add_u32_e32 v227, s77, v222
	v_add_u32_e32 v66, 0x80, v227
	v_add_u32_e32 v68, 0x81, v227
	v_add_u32_e32 v70, 0x82, v227
	v_add_u32_e32 v72, 0x83, v227
	v_med3_i32 v67, v66, s39, v198
	v_med3_i32 v66, v66, s33, v199
	v_med3_i32 v69, v68, s39, v198
	v_med3_i32 v68, v68, s33, v199
	v_med3_i32 v71, v70, s39, v198
	v_med3_i32 v70, v70, s33, v199
	v_med3_i32 v73, v72, s39, v198
	v_med3_i32 v72, v72, s33, v199
	v_lshl_add_u32 v67, v67, 2, s76
	v_lshl_add_u32 v66, v66, 2, s76
	v_lshl_add_u32 v69, v69, 2, s76
	v_lshl_add_u32 v68, v68, 2, s76
	v_lshl_add_u32 v70, v70, 2, s76
	v_lshl_add_u32 v72, v72, 2, s76
	v_lshl_add_u32 v71, v71, 2, s76
	v_lshl_add_u32 v73, v73, 2, s76
	ds_read_b32 v194, v67 offset:516
	ds_read_b32 v66, v66 offset:644
	ds_read_b32 v195, v69 offset:516
	ds_read_b32 v67, v68 offset:644
	ds_read_b32 v231, v71 offset:516
	ds_read_b32 v68, v70 offset:644
	ds_read_b32 v232, v73 offset:516
	ds_read_b32 v69, v72 offset:644
	v_add_u32_e32 v70, 0x88, v227
	v_add_u32_e32 v72, 0x89, v227
	v_add_u32_e32 v74, 0x8a, v227
	v_add_u32_e32 v76, 0x8b, v227
	v_med3_i32 v71, v70, s39, v198
	v_med3_i32 v70, v70, s33, v199
	v_med3_i32 v73, v72, s39, v198
	v_med3_i32 v72, v72, s33, v199
	v_med3_i32 v75, v74, s39, v198
	v_med3_i32 v74, v74, s33, v199
	v_med3_i32 v77, v76, s39, v198
	v_med3_i32 v76, v76, s33, v199
	v_lshl_add_u32 v71, v71, 2, s76
	v_lshl_add_u32 v70, v70, 2, s76
	v_lshl_add_u32 v73, v73, 2, s76
	v_lshl_add_u32 v72, v72, 2, s76
	v_lshl_add_u32 v74, v74, 2, s76
	v_lshl_add_u32 v76, v76, 2, s76
	v_lshl_add_u32 v75, v75, 2, s76
	v_lshl_add_u32 v77, v77, 2, s76
	ds_read_b32 v233, v71 offset:516
	ds_read_b32 v70, v70 offset:644
	ds_read_b32 v234, v73 offset:516
	ds_read_b32 v71, v72 offset:644
	ds_read_b32 v235, v75 offset:516
	ds_read_b32 v72, v74 offset:644
	ds_read_b32 v236, v77 offset:516
	ds_read_b32 v73, v76 offset:644
	v_add_u32_e32 v74, 0x90, v227
	v_add_u32_e32 v76, 0x91, v227
	v_add_u32_e32 v78, 0x92, v227
	v_add_u32_e32 v80, 0x93, v227
	v_med3_i32 v75, v74, s39, v198
	v_med3_i32 v74, v74, s33, v199
	v_med3_i32 v77, v76, s39, v198
	v_med3_i32 v76, v76, s33, v199
	v_med3_i32 v79, v78, s39, v198
	v_med3_i32 v78, v78, s33, v199
	v_med3_i32 v81, v80, s39, v198
	v_med3_i32 v80, v80, s33, v199
	v_lshl_add_u32 v75, v75, 2, s76
	v_lshl_add_u32 v74, v74, 2, s76
	v_lshl_add_u32 v77, v77, 2, s76
	v_lshl_add_u32 v76, v76, 2, s76
	v_lshl_add_u32 v78, v78, 2, s76
	v_lshl_add_u32 v80, v80, 2, s76
	v_lshl_add_u32 v79, v79, 2, s76
	v_lshl_add_u32 v81, v81, 2, s76
	ds_read_b32 v237, v75 offset:516
	ds_read_b32 v74, v74 offset:644
	ds_read_b32 v238, v77 offset:516
	ds_read_b32 v75, v76 offset:644
	ds_read_b32 v239, v79 offset:516
	ds_read_b32 v76, v78 offset:644
	ds_read_b32 v240, v81 offset:516
	ds_read_b32 v77, v80 offset:644
	v_add_u32_e32 v78, 0x98, v227
	v_add_u32_e32 v80, 0x99, v227
	v_add_u32_e32 v82, 0x9a, v227
	v_med3_i32 v79, v78, s39, v198
	v_med3_i32 v78, v78, s33, v199
	v_med3_i32 v81, v80, s39, v198
	v_med3_i32 v80, v80, s33, v199
	v_med3_i32 v83, v82, s39, v198
	v_med3_i32 v82, v82, s33, v199
	v_add_u32_e32 v84, 0x9b, v227
	s_waitcnt lgkmcnt(14)
; template <int MODE>
; __device__ __forceinline__ void partialSM(f32x16& p0, f32x16& p1, float& m_reg, float& mn, float& alpha, int relh, int relw_min, int relw_max, const float* lut) {
;     ...
;     if (nearT) {
; #pragma unroll
;       for (int r = 0; r < 16; ++r) { const int i0 = relh + (r & 3) + 8 * (r >> 2);
;         const int a0 = min(max(i0, -129), 129) + 129, a1 = min(max(i0 + 32, -129), 129) + 129;
;         p0[r] = fmaf(p0[r], C, lut[a0]); p1[r] = fmaf(p1[r], C, lut[a1]); }
;     } else {
; #pragma unroll
;       for (int r = 0; r < 16; ++r) { p0[r] = fmaf(p0[r], C, cfar); p1[r] = fmaf(p1[r], C, cfar); }
;     }
;     float pmax = p0[0];
; #pragma unroll
;     for (int r = 1; r < 16; ++r) pmax = fmaxf(pmax, p0[r]);
; #pragma unroll
;     for (int r = 0; r < 16; ++r) pmax = fmaxf(pmax, p1[r]);
;     { auto rr = __builtin_amdgcn_permlane32_swap(__float_as_uint(pmax), __float_as_uint(pmax), false, false);
;       pmax = fmaxf(__uint_as_float(rr[0]), __uint_as_float(rr[1])); }
;     if (__builtin_expect(__all(pmax - m_reg <= THR2), 1)) { mn = m_reg; alpha = 1.f; }
;     else { mn = fmaxf(m_reg, pmax); alpha = __builtin_amdgcn_exp2f(m_reg - mn); m_reg = mn; }
; #pragma unroll
;     for (int r = 0; r < 16; ++r) p0[r] = __builtin_amdgcn_exp2f(p0[r] - mn);
; #pragma unroll
;     for (int r = 0; r < 16; ++r) p1[r] = p1[r] - mn;
	v_fmac_f32_e32 v194, 0x3e38aa3b, v114
	v_fmac_f32_e32 v195, 0x3e38aa3b, v115
	v_lshl_add_u32 v79, v79, 2, s76
	v_lshl_add_u32 v78, v78, 2, s76
	v_lshl_add_u32 v81, v81, 2, s76
	v_lshl_add_u32 v80, v80, 2, s76
	v_lshl_add_u32 v82, v82, 2, s76
	v_med3_i32 v85, v84, s39, v198
	v_med3_i32 v84, v84, s33, v199
	v_fmac_f32_e32 v231, 0x3e38aa3b, v116
	v_fmac_f32_e32 v232, 0x3e38aa3b, v117
	v_lshl_add_u32 v83, v83, 2, s76
	v_lshl_add_u32 v85, v85, 2, s76
	v_lshl_add_u32 v84, v84, 2, s76
	ds_read_b32 v227, v79 offset:516
	ds_read_b32 v78, v78 offset:644
	ds_read_b32 v241, v81 offset:516
	ds_read_b32 v79, v80 offset:644
	ds_read_b32 v242, v83 offset:516
	ds_read_b32 v80, v82 offset:644
	ds_read_b32 v243, v85 offset:516
	ds_read_b32 v81, v84 offset:644
	v_max_f32_e32 v82, v194, v195
	v_fmac_f32_e32 v233, 0x3e38aa3b, v118
	s_waitcnt lgkmcnt(14)
	v_fmac_f32_e32 v234, 0x3e38aa3b, v119
	v_max3_f32 v82, v82, v231, v232
	v_fmac_f32_e32 v235, 0x3e38aa3b, v120
	v_fmac_f32_e32 v236, 0x3e38aa3b, v121
	v_max3_f32 v82, v82, v233, v234
	v_fmac_f32_e32 v237, 0x3e38aa3b, v122
	s_waitcnt lgkmcnt(13)
	v_fmac_f32_e32 v238, 0x3e38aa3b, v123
	v_max3_f32 v82, v82, v235, v236
	s_waitcnt lgkmcnt(11)
	v_fmac_f32_e32 v239, 0x3e38aa3b, v124
	s_waitcnt lgkmcnt(9)
	v_fmac_f32_e32 v240, 0x3e38aa3b, v125
	v_max3_f32 v82, v82, v237, v238
	s_waitcnt lgkmcnt(7)
	v_fmac_f32_e32 v227, 0x3e38aa3b, v126
	s_waitcnt lgkmcnt(5)
	v_fmac_f32_e32 v241, 0x3e38aa3b, v127
	v_max3_f32 v82, v82, v239, v240
	s_waitcnt lgkmcnt(3)
	v_fmac_f32_e32 v242, 0x3e38aa3b, v128
	s_waitcnt lgkmcnt(1)
	v_fmac_f32_e32 v243, 0x3e38aa3b, v129
	v_max3_f32 v82, v82, v227, v241
	v_max3_f32 v84, v82, v242, v243
	v_pk_fma_f32 v[82:83], v[98:99], s[48:49], v[66:67] op_sel_hi:[1,0,1]
	v_pk_fma_f32 v[86:87], v[102:103], s[48:49], v[70:71] op_sel_hi:[1,0,1]
	v_max3_f32 v66, v84, v82, v83
	v_pk_fma_f32 v[84:85], v[100:101], s[48:49], v[68:69] op_sel_hi:[1,0,1]
	v_pk_fma_f32 v[88:89], v[104:105], s[48:49], v[72:73] op_sel_hi:[1,0,1]
	v_max3_f32 v66, v66, v84, v85
	v_max3_f32 v66, v66, v86, v87
	v_max3_f32 v66, v66, v88, v89
	v_pk_fma_f32 v[90:91], v[106:107], s[48:49], v[74:75] op_sel_hi:[1,0,1]
	v_pk_fma_f32 v[92:93], v[108:109], s[48:49], v[76:77] op_sel_hi:[1,0,1]
	v_max3_f32 v66, v66, v90, v91
	v_max3_f32 v66, v66, v92, v93
	v_pk_fma_f32 v[94:95], v[110:111], s[48:49], v[78:79] op_sel_hi:[1,0,1]
	s_waitcnt lgkmcnt(0)
	v_pk_fma_f32 v[96:97], v[112:113], s[48:49], v[80:81] op_sel_hi:[1,0,1]
	v_max3_f32 v66, v66, v94, v95
	v_max3_f32 v66, v66, v96, v97
	v_mov_b32_e32 v67, v66
	s_nop 1
	v_permlane32_swap_b32_e32 v66, v67
	v_max_f32_e32 v66, v66, v67
	v_sub_f32_e32 v67, v66, v228
	v_cmp_ge_f32_e32 vcc, s94, v67
	v_max_f32_e32 v66, v228, v66
	v_sub_f32_e32 v67, v228, v66
	v_exp_f32_e32 v67, v67
	s_cmp_eq_u64 vcc, exec
	s_cselect_b64 vcc, -1, 0
	v_cndmask_b32_e32 v219, v66, v228, vcc
	v_cndmask_b32_e64 v225, v67, 1.0, vcc
	v_sub_f32_e32 v66, v194, v219
	v_sub_f32_e32 v67, v195, v219
	v_sub_f32_e32 v68, v231, v219
	v_sub_f32_e32 v69, v232, v219
	v_sub_f32_e32 v70, v233, v219
	v_sub_f32_e32 v71, v234, v219
	v_sub_f32_e32 v72, v235, v219
	v_sub_f32_e32 v73, v236, v219
	v_sub_f32_e32 v74, v237, v219
	v_sub_f32_e32 v75, v238, v219
	v_sub_f32_e32 v76, v239, v219
	v_sub_f32_e32 v77, v240, v219
	v_sub_f32_e32 v78, v227, v219
	v_sub_f32_e32 v79, v241, v219
	v_sub_f32_e32 v80, v242, v219
	v_sub_f32_e32 v81, v243, v219
	v_exp_f32_e32 v66, v66
	v_exp_f32_e32 v67, v67
	v_exp_f32_e32 v68, v68
	v_exp_f32_e32 v69, v69
	v_exp_f32_e32 v70, v70
	v_exp_f32_e32 v71, v71
	v_exp_f32_e32 v72, v72
	v_exp_f32_e32 v73, v73
	v_exp_f32_e32 v74, v74
	v_exp_f32_e32 v75, v75
	v_exp_f32_e32 v76, v76
	v_exp_f32_e32 v77, v77
	v_exp_f32_e32 v78, v78
	v_exp_f32_e32 v79, v79
	v_exp_f32_e32 v80, v80
	v_exp_f32_e32 v81, v81
	v_sub_f32_e32 v97, v97, v219
	v_sub_f32_e32 v96, v96, v219
	v_sub_f32_e32 v95, v95, v219
	v_sub_f32_e32 v94, v94, v219
	v_sub_f32_e32 v93, v93, v219
	v_sub_f32_e32 v92, v92, v219
	v_sub_f32_e32 v91, v91, v219
	v_sub_f32_e32 v90, v90, v219
	v_sub_f32_e32 v89, v89, v219
	v_sub_f32_e32 v88, v88, v219
	v_sub_f32_e32 v87, v87, v219
	v_sub_f32_e32 v86, v86, v219
	v_sub_f32_e32 v85, v85, v219
	v_sub_f32_e32 v84, v84, v219
	v_sub_f32_e32 v83, v83, v219
	v_sub_f32_e32 v82, v82, v219
	s_xor_b64 s[72:73], exec, -1

; #define SBAR() __builtin_amdgcn_sched_barrier(0)
; __device__ __forceinline__ void finishSM(f32x16& p0, f32x16& p1, float alpha, float& l_reg, bf16x8& pa0, bf16x8& pa1, bf16x8& pa2, bf16x8& pa3) {
; #pragma unroll
;   for (int r = 0; r < 16; ++r) p1[r] = __builtin_amdgcn_exp2f(p1[r]);
;   float ps = 0;
; #pragma unroll
;   for (int r = 0; r < 16; ++r) ps += p0[r];
; #pragma unroll
;   for (int r = 0; r < 16; ++r) ps += p1[r];
;   { auto rr = __builtin_amdgcn_permlane32_swap(__float_as_uint(ps), __float_as_uint(ps), false, false);
;     ps = __uint_as_float(rr[0]) + __uint_as_float(rr[1]); }
;   l_reg = l_reg * alpha + ps;
;     ...
;   PK4(p0, 0, pa0); PK4(p0, 8, pa1); PK4(p1, 0, pa2); PK4(p1, 8, pa3);
;     ...
; }
; template <int ND0, int DOFF>
; __device__ __forceinline__ void qkt(f32x16& p0, f32x16& p1, const char* Ks, const bf16x8* qr, int r32, int hi) {
;   p0 = f32x16{}; p1 = f32x16{};
; #pragma unroll
;   for (int d0 = 0; d0 < ND0; ++d0) { const int cb = ((d0 + DOFF) * 16 + hi * 8) * 2;
;     bf16x8 b0 = *reinterpret_cast<const bf16x8*>(Ks + KSWZ(r32, cb));
;     bf16x8 b1 = *reinterpret_cast<const bf16x8*>(Ks + KSWZ(32 + r32, cb));
;     p0 = __builtin_amdgcn_mfma_f32_32x32x16_bf16(b0, qr[d0], p0, 0, 0, 0);
;     p1 = __builtin_amdgcn_mfma_f32_32x32x16_bf16(b1, qr[d0], p1, 0, 0, 0); }
; }
; __device__ __forceinline__ int v_st(int k, int c) { const int kk = (k & ~0xC) | ((k & 4) << 1) | ((k & 8) >> 1); return ((kk >> 3) * 4 + (c >> 5)) * 512 + ((kk & 7) * 32 + (c & 31)) * 2; }
; __device__ __forceinline__ int v_rd_base(int lane) { return ((lane & 3) << 3) | (((lane >> 2) & 3) << 6) | (((lane >> 4) & 1) << 5) | (((lane >> 5) & 1) << 8); }
; template <int OFF> __device__ __forceinline__ s16x4 tr_read(int vb) {
;   s16x4 r; asm volatile("ds_read_b64_tr_b16 %0, %1 offset:%2" : "=&v"(r) : "v"(vb), "i"(OFF) : "memory"); return r;
; }
; template <int D0> __device__ __forceinline__ void pv_one(f32x16& od, int vb, bf16x8 pa0, bf16x8 pa1, bf16x8 pa2, bf16x8 pa3) {
;   const s16x4 l0 = tr_read<v_rd_off(D0, 0, 0)>(vb), h0 = tr_read<v_rd_off(D0, 0, 1)>(vb), l1 = tr_read<v_rd_off(D0, 1, 0)>(vb), h1 = tr_read<v_rd_off(D0, 1, 1)>(vb);
;   const s16x4 l2 = tr_read<v_rd_off(D0, 2, 0)>(vb), h2 = tr_read<v_rd_off(D0, 2, 1)>(vb), l3 = tr_read<v_rd_off(D0, 3, 0)>(vb), h3 = tr_read<v_rd_off(D0, 3, 1)>(vb);
;   asm volatile("s_waitcnt lgkmcnt(0)" ::: "memory"); SBAR();
.LBB0_177:
	v_readfirstlane_b32 s20, v224
	v_readfirstlane_b32 s21, v223
	s_nop 3
	s_add_i32 s22, s20, s77
	s_addk_i32 s22, 0x7f
	s_add_i32 s23, s21, s77
	s_addk_i32 s23, 0x40
	s_add_i32 s24, s22, 64
	s_add_i32 s25, s23, 64
	s_mov_b32 s2, s0
	s_waitcnt lgkmcnt(0)
	s_barrier
	s_add_i32 s0, s68, 0
	v_add_u32_e32 v0, s0, v216
	ds_read_b128 v[98:101], v0 offset:49152
	ds_read_b128 v[102:105], v0 offset:57344
	v_add_u32_e32 v0, s0, v217
	ds_read_b128 v[162:165], v0 offset:49152
	ds_read_b128 v[166:169], v0 offset:57344
	v_add_u32_e32 v0, s0, v218
	s_waitcnt lgkmcnt(3)
	v_mfma_f32_32x32x16_bf16 v[114:129], v[98:101], v[142:145], 0
	s_waitcnt lgkmcnt(2)
	v_mfma_f32_32x32x16_bf16 v[98:113], v[102:105], v[142:145], 0
	s_waitcnt lgkmcnt(1)
	v_mfma_f32_32x32x16_bf16 v[114:129], v[162:165], v[138:141], v[114:129]
	s_waitcnt lgkmcnt(0)
	v_mfma_f32_32x32x16_bf16 v[98:113], v[166:169], v[138:141], v[98:113]
	ds_read_b128 v[162:165], v0 offset:49152
	ds_read_b128 v[166:169], v0 offset:57344
	v_add_u32_e32 v0, s0, v219
	s_waitcnt lgkmcnt(1)
	v_mfma_f32_32x32x16_bf16 v[114:129], v[162:165], v[134:137], v[114:129]
	s_waitcnt lgkmcnt(0)
	v_mfma_f32_32x32x16_bf16 v[98:113], v[166:169], v[134:137], v[98:113]
	ds_read_b128 v[162:165], v0 offset:49152
	ds_read_b128 v[166:169], v0 offset:57344
	v_exp_f32_e32 v0, v82
	v_exp_f32_e32 v82, v83
	v_exp_f32_e32 v83, v84
	v_exp_f32_e32 v84, v85
	v_exp_f32_e32 v85, v86
	v_exp_f32_e32 v86, v87
	v_exp_f32_e32 v87, v88
	v_exp_f32_e32 v88, v89
	v_exp_f32_e32 v89, v90
	v_exp_f32_e32 v90, v91
	v_exp_f32_e32 v91, v92
	v_exp_f32_e32 v92, v93
	v_exp_f32_e32 v93, v94
	v_exp_f32_e32 v94, v95
	v_exp_f32_e32 v95, v96
	v_exp_f32_e32 v96, v97
	v_add_f32_e32 v97, v67, v66
	v_add_f32_e32 v97, v68, v97
	v_add_f32_e32 v97, v69, v97
	v_add_f32_e32 v97, v70, v97
	v_add_f32_e32 v97, v71, v97
	v_add_f32_e32 v97, v72, v97
	v_add_f32_e32 v97, v73, v97
	v_add_f32_e32 v97, v74, v97
	v_add_f32_e32 v97, v75, v97
	v_add_f32_e32 v97, v76, v97
	v_add_f32_e32 v97, v77, v97
	v_add_f32_e32 v97, v78, v97
	v_add_f32_e32 v97, v79, v97
	v_add_f32_e32 v97, v80, v97
	v_add_f32_e32 v97, v81, v97
	v_add_f32_e32 v97, v0, v97
	v_add_f32_e32 v97, v82, v97
	v_add_f32_e32 v97, v83, v97
	v_add_f32_e32 v97, v84, v97
	v_add_f32_e32 v97, v85, v97
	v_add_f32_e32 v97, v86, v97
	v_add_f32_e32 v97, v87, v97
	v_add_f32_e32 v97, v88, v97
	v_add_f32_e32 v97, v89, v97
	v_add_f32_e32 v97, v90, v97
	s_waitcnt lgkmcnt(1)
	v_mfma_f32_32x32x16_bf16 v[114:129], v[162:165], v[130:133], v[114:129]
	v_add_f32_e32 v97, v91, v97
	v_add_f32_e32 v97, v92, v97
	v_add_f32_e32 v97, v93, v97
	v_add_f32_e32 v97, v94, v97
	v_add_f32_e32 v97, v95, v97
	v_add_f32_e32 v226, v96, v97
	v_mov_b32_e32 v227, v226
	s_waitcnt lgkmcnt(0)
	v_mfma_f32_32x32x16_bf16 v[98:113], v[166:169], v[130:133], v[98:113]
	v_cvt_pk_bf16_f32 v66, v66, v67
	v_cvt_pk_bf16_f32 v67, v68, v69
	v_cvt_pk_bf16_f32 v68, v70, v71
	v_cvt_pk_bf16_f32 v69, v72, v73
	v_cvt_pk_bf16_f32 v70, v74, v75
	v_cvt_pk_bf16_f32 v71, v76, v77
	v_cvt_pk_bf16_f32 v72, v78, v79
	v_cvt_pk_bf16_f32 v73, v80, v81
	v_cvt_pk_bf16_f32 v74, v0, v82
	v_cvt_pk_bf16_f32 v75, v83, v84
	v_cvt_pk_bf16_f32 v76, v85, v86
	v_cvt_pk_bf16_f32 v77, v87, v88
	v_cvt_pk_bf16_f32 v78, v89, v90
	v_cvt_pk_bf16_f32 v79, v91, v92
	v_cvt_pk_bf16_f32 v80, v93, v94
	v_cvt_pk_bf16_f32 v81, v95, v96
	v_permlane32_swap_b32_e32 v226, v227
	v_permlane32_swap_b32_e32 v66, v68
	v_permlane32_swap_b32_e32 v67, v69
	v_permlane32_swap_b32_e32 v70, v72
	v_permlane32_swap_b32_e32 v71, v73
	v_permlane32_swap_b32_e32 v74, v76
	v_permlane32_swap_b32_e32 v75, v77
	v_permlane32_swap_b32_e32 v78, v80
	v_permlane32_swap_b32_e32 v79, v81
	v_add_co_u32_e32 v82, vcc, s4, v190
	s_nop 1
	v_addc_co_u32_e32 v83, vcc, -1, v191, vcc
	v_add_co_u32_e32 v84, vcc, s5, v190
	s_nop 1
	v_addc_co_u32_e32 v85, vcc, -1, v191, vcc
	global_load_dwordx4 v[162:165], v[82:83], off
	global_load_dwordx4 v[166:169], v[82:83], off offset:-512
	global_load_dwordx4 v[174:177], v[84:85], off
	global_load_dwordx4 v[170:173], v[84:85], off offset:-512
	v_add_u32_e32 v0, s66, v221
	ds_read_b64_tr_b16 v[82:83], v0 offset:0
	ds_read_b64_tr_b16 v[84:85], v0 offset:0x800
	ds_read_b64_tr_b16 v[86:87], v0 offset:0x1000
	ds_read_b64_tr_b16 v[88:89], v0 offset:0x1800
	ds_read_b64_tr_b16 v[90:91], v0 offset:0x2000
	ds_read_b64_tr_b16 v[92:93], v0 offset:0x2800
	ds_read_b64_tr_b16 v[94:95], v0 offset:0x3000
	ds_read_b64_tr_b16 v[96:97], v0 offset:0x3800
	s_waitcnt lgkmcnt(0)
	s_nop 0
	v_mfma_f32_32x32x16_bf16 v[50:65], v[66:69], v[82:85], v[50:65]
	ds_read_b64_tr_b16 v[82:83], v0 offset:0x200
	ds_read_b64_tr_b16 v[84:85], v0 offset:0xa00
	v_mfma_f32_32x32x16_bf16 v[50:65], v[70:73], v[86:89], v[50:65]
	ds_read_b64_tr_b16 v[86:87], v0 offset:0x1200
	ds_read_b64_tr_b16 v[88:89], v0 offset:0x1a00
	v_mfma_f32_32x32x16_bf16 v[50:65], v[74:77], v[90:93], v[50:65]
	ds_read_b64_tr_b16 v[90:91], v0 offset:0x2200
	ds_read_b64_tr_b16 v[92:93], v0 offset:0x2a00
	v_mfma_f32_32x32x16_bf16 v[50:65], v[78:81], v[94:97], v[50:65]
	ds_read_b64_tr_b16 v[94:95], v0 offset:0x3200
	ds_read_b64_tr_b16 v[96:97], v0 offset:0x3a00
	s_waitcnt lgkmcnt(0)
	v_mfma_f32_32x32x16_bf16 v[34:49], v[66:69], v[82:85], v[34:49]
	ds_read_b64_tr_b16 v[82:83], v0 offset:0x400
	ds_read_b64_tr_b16 v[84:85], v0 offset:0xc00
	v_mfma_f32_32x32x16_bf16 v[34:49], v[70:73], v[86:89], v[34:49]
	ds_read_b64_tr_b16 v[86:87], v0 offset:0x1400
	ds_read_b64_tr_b16 v[88:89], v0 offset:0x1c00
	v_mfma_f32_32x32x16_bf16 v[34:49], v[74:77], v[90:93], v[34:49]
	ds_read_b64_tr_b16 v[90:91], v0 offset:0x2400
	ds_read_b64_tr_b16 v[92:93], v0 offset:0x2c00
	v_mfma_f32_32x32x16_bf16 v[34:49], v[78:81], v[94:97], v[34:49]
	ds_read_b64_tr_b16 v[94:95], v0 offset:0x3400
	ds_read_b64_tr_b16 v[96:97], v0 offset:0x3c00
	s_waitcnt lgkmcnt(0)
	v_mfma_f32_32x32x16_bf16 v[18:33], v[66:69], v[82:85], v[18:33]
	ds_read_b64_tr_b16 v[82:83], v0 offset:0x600
	ds_read_b64_tr_b16 v[84:85], v0 offset:0xe00
	v_mfma_f32_32x32x16_bf16 v[18:33], v[70:73], v[86:89], v[18:33]
	ds_read_b64_tr_b16 v[86:87], v0 offset:0x1600
	ds_read_b64_tr_b16 v[88:89], v0 offset:0x1e00
	v_mfma_f32_32x32x16_bf16 v[18:33], v[74:77], v[90:93], v[18:33]
	ds_read_b64_tr_b16 v[90:91], v0 offset:0x2600
	ds_read_b64_tr_b16 v[92:93], v0 offset:0x2e00
	v_mfma_f32_32x32x16_bf16 v[18:33], v[78:81], v[94:97], v[18:33]
	ds_read_b64_tr_b16 v[94:95], v0 offset:0x3600
	ds_read_b64_tr_b16 v[96:97], v0 offset:0x3e00
	s_waitcnt lgkmcnt(0)
	v_mfma_f32_32x32x16_bf16 v[2:17], v[66:69], v[82:85], v[2:17]
	s_cmp_gt_i32 s95, s22
	s_cselect_b64 s[0:1], -1, 0
	s_cmp_lt_i32 s15, s22
	s_cselect_b64 vcc, -1, 0
	v_mov_b32_e32 v232, s76
	v_mfma_f32_32x32x16_bf16 v[2:17], v[70:73], v[86:89], v[2:17]
	v_mfma_f32_32x32x16_bf16 v[2:17], v[74:77], v[90:93], v[2:17]
	v_mfma_f32_32x32x16_bf16 v[2:17], v[78:81], v[94:97], v[2:17]
	s_and_saveexec_b64 s[58:59], vcc
	s_cbranch_execz .LBB0_181
; template <int MODE>
; __device__ __forceinline__ void partialSM(f32x16& p0, f32x16& p1, float& m_reg, float& mn, float& alpha, int relh, int relw_min, int relw_max, const float* lut) {
;     ...
;       if (relw_max <= -128) { nearT = false; cfar = lut[0]; }
;       else if (relw_min >= 128) { nearT = false; cfar = lut[258]; }
;       if (!nearT) {
;         float pmax = p0[0];
; #pragma unroll
;         for (int r = 1; r < 16; ++r) pmax = fmaxf(pmax, p0[r]);
; #pragma unroll
;         for (int r = 0; r < 16; ++r) pmax = fmaxf(pmax, p1[r]);
;         { auto rr = __builtin_amdgcn_permlane32_swap(__float_as_uint(pmax), __float_as_uint(pmax), false, false);
;           pmax = fmaxf(__uint_as_float(rr[0]), __uint_as_float(rr[1])); }
;         const float tmax = fmaf(pmax, C, cfar);
;         if (__builtin_expect(__all(tmax - m_reg <= THR2), 1)) { mn = m_reg; alpha = 1.f; }
;         else { mn = fmaxf(m_reg, tmax); alpha = __builtin_amdgcn_exp2f(m_reg - mn); m_reg = mn; }
;         const float off = cfar - mn;
; #pragma unroll
;         for (int r = 0; r < 16; ++r) p0[r] = fmaf(p0[r], C, off);
; #pragma unroll
;         for (int r = 0; r < 16; ++r) p1[r] = fmaf(p1[r], C, off);
; #pragma unroll
;         for (int r = 0; r < 16; ++r) p0[r] = __builtin_amdgcn_exp2f(p0[r]);
;         return;
;       }
;     }
;     if (nearT) {
; #pragma unroll
;       for (int r = 0; r < 16; ++r) { const int i0 = relh + (r & 3) + 8 * (r >> 2);
;         const int a0 = min(max(i0, -129), 129) + 129, a1 = min(max(i0 + 32, -129), 129) + 129;
;         p0[r] = fmaf(p0[r], C, lut[a0]); p1[r] = fmaf(p1[r], C, lut[a1]); }
	s_cmp_gt_i32 s91, s23
	s_cselect_b64 vcc, -1, 0
	s_mov_b64 s[62:63], -1
	s_and_saveexec_b64 s[60:61], vcc
	s_cbranch_execz .LBB0_180
	v_add_u32_e32 v230, s77, v225
	v_add_u32_e32 v66, 64, v230
	v_add_u32_e32 v68, 0x41, v230
	v_add_u32_e32 v70, 0x42, v230
	v_add_u32_e32 v72, 0x43, v230
	v_med3_i32 v67, v66, s39, v198
	v_med3_i32 v66, v66, s33, v199
	v_med3_i32 v69, v68, s39, v198
	v_med3_i32 v68, v68, s33, v199
	v_med3_i32 v71, v70, s39, v198
	v_med3_i32 v70, v70, s33, v199
	v_med3_i32 v73, v72, s39, v198
	v_med3_i32 v72, v72, s33, v199
	v_lshl_add_u32 v67, v67, 2, s76
	v_lshl_add_u32 v66, v66, 2, s76
	v_lshl_add_u32 v69, v69, 2, s76
	v_lshl_add_u32 v68, v68, 2, s76
	v_lshl_add_u32 v70, v70, 2, s76
	v_lshl_add_u32 v72, v72, 2, s76
	v_lshl_add_u32 v71, v71, 2, s76
	v_lshl_add_u32 v73, v73, 2, s76
	ds_read_b32 v194, v67 offset:516
	ds_read_b32 v66, v66 offset:644
	ds_read_b32 v195, v69 offset:516
	ds_read_b32 v67, v68 offset:644
	ds_read_b32 v232, v71 offset:516
	ds_read_b32 v68, v70 offset:644
	ds_read_b32 v233, v73 offset:516
	ds_read_b32 v69, v72 offset:644
	v_add_u32_e32 v70, 0x48, v230
	v_add_u32_e32 v72, 0x49, v230
	v_add_u32_e32 v74, 0x4a, v230
	v_add_u32_e32 v76, 0x4b, v230
	v_med3_i32 v71, v70, s39, v198
	v_med3_i32 v70, v70, s33, v199
	v_med3_i32 v73, v72, s39, v198
	v_med3_i32 v72, v72, s33, v199
	v_med3_i32 v75, v74, s39, v198
	v_med3_i32 v74, v74, s33, v199
	v_med3_i32 v77, v76, s39, v198
	v_med3_i32 v76, v76, s33, v199
	v_lshl_add_u32 v71, v71, 2, s76
	v_lshl_add_u32 v70, v70, 2, s76
	v_lshl_add_u32 v73, v73, 2, s76
	v_lshl_add_u32 v72, v72, 2, s76
	v_lshl_add_u32 v74, v74, 2, s76
	v_lshl_add_u32 v76, v76, 2, s76
	v_lshl_add_u32 v75, v75, 2, s76
	v_lshl_add_u32 v77, v77, 2, s76
	ds_read_b32 v234, v71 offset:516
	ds_read_b32 v70, v70 offset:644
	ds_read_b32 v235, v73 offset:516
	ds_read_b32 v71, v72 offset:644
	ds_read_b32 v236, v75 offset:516
	ds_read_b32 v72, v74 offset:644
	ds_read_b32 v237, v77 offset:516
	ds_read_b32 v73, v76 offset:644
	v_add_u32_e32 v74, 0x50, v230
	v_add_u32_e32 v76, 0x51, v230
	v_add_u32_e32 v78, 0x52, v230
	v_add_u32_e32 v80, 0x53, v230
	v_med3_i32 v75, v74, s39, v198
	v_med3_i32 v74, v74, s33, v199
	v_med3_i32 v77, v76, s39, v198
	v_med3_i32 v76, v76, s33, v199
	v_med3_i32 v79, v78, s39, v198
	v_med3_i32 v78, v78, s33, v199
	v_med3_i32 v81, v80, s39, v198
	v_med3_i32 v80, v80, s33, v199
	v_lshl_add_u32 v75, v75, 2, s76
	v_lshl_add_u32 v74, v74, 2, s76
	v_lshl_add_u32 v77, v77, 2, s76
	v_lshl_add_u32 v76, v76, 2, s76
	v_lshl_add_u32 v78, v78, 2, s76
	v_lshl_add_u32 v80, v80, 2, s76
	v_lshl_add_u32 v79, v79, 2, s76
	v_lshl_add_u32 v81, v81, 2, s76
	ds_read_b32 v238, v75 offset:516
	ds_read_b32 v74, v74 offset:644
	ds_read_b32 v239, v77 offset:516
	ds_read_b32 v75, v76 offset:644
	ds_read_b32 v240, v79 offset:516
	ds_read_b32 v76, v78 offset:644
	ds_read_b32 v241, v81 offset:516
	ds_read_b32 v77, v80 offset:644
	v_add_u32_e32 v78, 0x58, v230
	v_add_u32_e32 v80, 0x59, v230
	v_add_u32_e32 v82, 0x5a, v230
	v_med3_i32 v79, v78, s39, v198
	v_med3_i32 v78, v78, s33, v199
	v_med3_i32 v81, v80, s39, v198
	v_med3_i32 v80, v80, s33, v199
	v_med3_i32 v83, v82, s39, v198
	v_med3_i32 v82, v82, s33, v199
	v_add_u32_e32 v84, 0x5b, v230
	s_waitcnt lgkmcnt(14)
	v_fmac_f32_e32 v194, 0x3e38aa3b, v114
	v_fmac_f32_e32 v195, 0x3e38aa3b, v115
	v_lshl_add_u32 v79, v79, 2, s76
	v_lshl_add_u32 v78, v78, 2, s76
	v_lshl_add_u32 v81, v81, 2, s76
	v_lshl_add_u32 v80, v80, 2, s76
	v_lshl_add_u32 v82, v82, 2, s76
	v_med3_i32 v85, v84, s39, v198
	v_med3_i32 v84, v84, s33, v199
	v_fmac_f32_e32 v232, 0x3e38aa3b, v116
	v_fmac_f32_e32 v233, 0x3e38aa3b, v117
	v_lshl_add_u32 v83, v83, 2, s76
	v_lshl_add_u32 v85, v85, 2, s76
	v_lshl_add_u32 v84, v84, 2, s76
	ds_read_b32 v242, v79 offset:516
	ds_read_b32 v78, v78 offset:644
	ds_read_b32 v243, v81 offset:516
	ds_read_b32 v79, v80 offset:644
	ds_read_b32 v244, v83 offset:516
	ds_read_b32 v80, v82 offset:644
	ds_read_b32 v245, v85 offset:516
	ds_read_b32 v81, v84 offset:644
	v_max_f32_e32 v82, v194, v195
	v_fmac_f32_e32 v234, 0x3e38aa3b, v118
	s_waitcnt lgkmcnt(14)
; template <int MODE>
; __device__ __forceinline__ void partialSM(f32x16& p0, f32x16& p1, float& m_reg, float& mn, float& alpha, int relh, int relw_min, int relw_max, const float* lut) {
;     ...
;     if (nearT) {
; #pragma unroll
;       for (int r = 0; r < 16; ++r) { const int i0 = relh + (r & 3) + 8 * (r >> 2);
;         const int a0 = min(max(i0, -129), 129) + 129, a1 = min(max(i0 + 32, -129), 129) + 129;
;         p0[r] = fmaf(p0[r], C, lut[a0]); p1[r] = fmaf(p1[r], C, lut[a1]); }
;     } else {
; #pragma unroll
;       for (int r = 0; r < 16; ++r) { p0[r] = fmaf(p0[r], C, cfar); p1[r] = fmaf(p1[r], C, cfar); }
;     }
;     float pmax = p0[0];
; #pragma unroll
;     for (int r = 1; r < 16; ++r) pmax = fmaxf(pmax, p0[r]);
; #pragma unroll
;     for (int r = 0; r < 16; ++r) pmax = fmaxf(pmax, p1[r]);
;     { auto rr = __builtin_amdgcn_permlane32_swap(__float_as_uint(pmax), __float_as_uint(pmax), false, false);
;       pmax = fmaxf(__uint_as_float(rr[0]), __uint_as_float(rr[1])); }
;     if (__builtin_expect(__all(pmax - m_reg <= THR2), 1)) { mn = m_reg; alpha = 1.f; }
;     else { mn = fmaxf(m_reg, pmax); alpha = __builtin_amdgcn_exp2f(m_reg - mn); m_reg = mn; }
; #pragma unroll
;     for (int r = 0; r < 16; ++r) p0[r] = __builtin_amdgcn_exp2f(p0[r] - mn);
; #pragma unroll
;     for (int r = 0; r < 16; ++r) p1[r] = p1[r] - mn;
	v_fmac_f32_e32 v235, 0x3e38aa3b, v119
	v_max3_f32 v82, v82, v232, v233
	v_fmac_f32_e32 v236, 0x3e38aa3b, v120
	v_fmac_f32_e32 v237, 0x3e38aa3b, v121
	v_max3_f32 v82, v82, v234, v235
	v_fmac_f32_e32 v238, 0x3e38aa3b, v122
	s_waitcnt lgkmcnt(13)
	v_fmac_f32_e32 v239, 0x3e38aa3b, v123
	v_max3_f32 v82, v82, v236, v237
	s_waitcnt lgkmcnt(11)
	v_fmac_f32_e32 v240, 0x3e38aa3b, v124
	s_waitcnt lgkmcnt(9)
	v_fmac_f32_e32 v241, 0x3e38aa3b, v125
	v_max3_f32 v82, v82, v238, v239
	s_waitcnt lgkmcnt(7)
	v_fmac_f32_e32 v242, 0x3e38aa3b, v126
	s_waitcnt lgkmcnt(5)
	v_fmac_f32_e32 v243, 0x3e38aa3b, v127
	v_max3_f32 v82, v82, v240, v241
	s_waitcnt lgkmcnt(3)
	v_fmac_f32_e32 v244, 0x3e38aa3b, v128
	s_waitcnt lgkmcnt(1)
	v_fmac_f32_e32 v245, 0x3e38aa3b, v129
	v_max3_f32 v82, v82, v242, v243
	v_max3_f32 v84, v82, v244, v245
	v_pk_fma_f32 v[82:83], v[98:99], s[48:49], v[66:67] op_sel_hi:[1,0,1]
	v_pk_fma_f32 v[86:87], v[102:103], s[48:49], v[70:71] op_sel_hi:[1,0,1]
	v_max3_f32 v66, v84, v82, v83
	v_pk_fma_f32 v[84:85], v[100:101], s[48:49], v[68:69] op_sel_hi:[1,0,1]
	v_pk_fma_f32 v[88:89], v[104:105], s[48:49], v[72:73] op_sel_hi:[1,0,1]
	v_max3_f32 v66, v66, v84, v85
	v_max3_f32 v66, v66, v86, v87
	v_max3_f32 v66, v66, v88, v89
	v_pk_fma_f32 v[90:91], v[106:107], s[48:49], v[74:75] op_sel_hi:[1,0,1]
	v_pk_fma_f32 v[92:93], v[108:109], s[48:49], v[76:77] op_sel_hi:[1,0,1]
	v_max3_f32 v66, v66, v90, v91
	v_max3_f32 v66, v66, v92, v93
	v_pk_fma_f32 v[94:95], v[110:111], s[48:49], v[78:79] op_sel_hi:[1,0,1]
	s_waitcnt lgkmcnt(0)
	v_pk_fma_f32 v[96:97], v[112:113], s[48:49], v[80:81] op_sel_hi:[1,0,1]
	v_max3_f32 v66, v66, v94, v95
	v_max3_f32 v66, v66, v96, v97
	v_mov_b32_e32 v67, v66
	s_nop 1
	v_permlane32_swap_b32_e32 v66, v67
	v_max_f32_e32 v66, v66, v67
	v_sub_f32_e32 v67, v66, v222
	v_cmp_ge_f32_e32 vcc, s94, v67
	v_max_f32_e32 v66, v222, v66
	v_sub_f32_e32 v67, v222, v66
	v_exp_f32_e32 v67, v67
	s_cmp_eq_u64 vcc, exec
	s_cselect_b64 vcc, -1, 0
	v_cndmask_b32_e32 v231, v66, v222, vcc
	v_cndmask_b32_e64 v229, v67, 1.0, vcc
	v_sub_f32_e32 v66, v194, v231
	v_sub_f32_e32 v67, v195, v231
	v_sub_f32_e32 v68, v232, v231
	v_sub_f32_e32 v69, v233, v231
	v_sub_f32_e32 v70, v234, v231
	v_sub_f32_e32 v71, v235, v231
	v_sub_f32_e32 v72, v236, v231
	v_sub_f32_e32 v73, v237, v231
	v_sub_f32_e32 v74, v238, v231
	v_sub_f32_e32 v75, v239, v231
	v_sub_f32_e32 v76, v240, v231
	v_sub_f32_e32 v77, v241, v231
	v_sub_f32_e32 v78, v242, v231
	v_sub_f32_e32 v79, v243, v231
	v_sub_f32_e32 v80, v244, v231
	v_sub_f32_e32 v81, v245, v231
	v_exp_f32_e32 v66, v66
	v_exp_f32_e32 v67, v67
	v_exp_f32_e32 v68, v68
	v_exp_f32_e32 v69, v69
	v_exp_f32_e32 v70, v70
	v_exp_f32_e32 v71, v71
	v_exp_f32_e32 v72, v72
	v_exp_f32_e32 v73, v73
	v_exp_f32_e32 v74, v74
	v_exp_f32_e32 v75, v75
	v_exp_f32_e32 v76, v76
	v_exp_f32_e32 v77, v77
	v_exp_f32_e32 v78, v78
	v_exp_f32_e32 v79, v79
	v_exp_f32_e32 v80, v80
	v_exp_f32_e32 v81, v81
	v_sub_f32_e32 v97, v97, v231
	v_sub_f32_e32 v96, v96, v231
	v_sub_f32_e32 v95, v95, v231
	v_sub_f32_e32 v94, v94, v231
	v_sub_f32_e32 v93, v93, v231
	v_sub_f32_e32 v92, v92, v231
	v_sub_f32_e32 v91, v91, v231
	v_sub_f32_e32 v90, v90, v231
	v_sub_f32_e32 v89, v89, v231
	v_sub_f32_e32 v88, v88, v231
	v_sub_f32_e32 v87, v87, v231
	v_sub_f32_e32 v86, v86, v231
	v_sub_f32_e32 v85, v85, v231
	v_sub_f32_e32 v84, v84, v231
	v_sub_f32_e32 v83, v83, v231
	v_sub_f32_e32 v82, v82, v231
	s_xor_b64 s[62:63], exec, -1

; template <int MODE>
; __device__ __forceinline__ void partialSM(f32x16& p0, f32x16& p1, float& m_reg, float& mn, float& alpha, int relh, int relw_min, int relw_max, const float* lut) {
;     ...
;       if (relw_max <= -128) { nearT = false; cfar = lut[0]; }
;       else if (relw_min >= 128) { nearT = false; cfar = lut[258]; }
;       if (!nearT) {
;         float pmax = p0[0];
; #pragma unroll
;         for (int r = 1; r < 16; ++r) pmax = fmaxf(pmax, p0[r]);
; #pragma unroll
;         for (int r = 0; r < 16; ++r) pmax = fmaxf(pmax, p1[r]);
;         { auto rr = __builtin_amdgcn_permlane32_swap(__float_as_uint(pmax), __float_as_uint(pmax), false, false);
;           pmax = fmaxf(__uint_as_float(rr[0]), __uint_as_float(rr[1])); }
;         const float tmax = fmaf(pmax, C, cfar);
;         if (__builtin_expect(__all(tmax - m_reg <= THR2), 1)) { mn = m_reg; alpha = 1.f; }
;         else { mn = fmaxf(m_reg, tmax); alpha = __builtin_amdgcn_exp2f(m_reg - mn); m_reg = mn; }
;         const float off = cfar - mn;
; #pragma unroll
; template <int OFF> __device__ __forceinline__ s16x4 tr_read(int vb) {
;   s16x4 r; asm volatile("ds_read_b64_tr_b16 %0, %1 offset:%2" : "=&v"(r) : "v"(vb), "i"(OFF) : "memory"); return r;
; }
; template <int D0> __device__ __forceinline__ void pv_one(f32x16& od, int vb, bf16x8 pa0, bf16x8 pa1, bf16x8 pa2, bf16x8 pa3) {
;   const s16x4 l0 = tr_read<v_rd_off(D0, 0, 0)>(vb), h0 = tr_read<v_rd_off(D0, 0, 1)>(vb), l1 = tr_read<v_rd_off(D0, 1, 0)>(vb), h1 = tr_read<v_rd_off(D0, 1, 1)>(vb);
;   const s16x4 l2 = tr_read<v_rd_off(D0, 2, 0)>(vb), h2 = tr_read<v_rd_off(D0, 2, 1)>(vb), l3 = tr_read<v_rd_off(D0, 3, 0)>(vb), h3 = tr_read<v_rd_off(D0, 3, 1)>(vb);
;   asm volatile("s_waitcnt lgkmcnt(0)" ::: "memory"); SBAR();
;     ...
;   od = __builtin_amdgcn_mfma_f32_32x32x16_bf16(pa0, PK(l0, h0), od, 0, 0, 0);
;   od = __builtin_amdgcn_mfma_f32_32x32x16_bf16(pa1, PK(l1, h1), od, 0, 0, 0);
;   od = __builtin_amdgcn_mfma_f32_32x32x16_bf16(pa2, PK(l2, h2), od, 0, 0, 0);
;   od = __builtin_amdgcn_mfma_f32_32x32x16_bf16(pa3, PK(l3, h3), od, 0, 0, 0);
;     ...
; }
; __device__ __forceinline__ void pv_d0(f32x16* o, int vb, bf16x8 pa0, bf16x8 pa1, bf16x8 pa2, bf16x8 pa3) {
;   pv_one<0>(o[0], vb, pa0, pa1, pa2, pa3); pv_one<1>(o[1], vb, pa0, pa1, pa2, pa3); pv_one<2>(o[2], vb, pa0, pa1, pa2, pa3); pv_one<3>(o[3], vb, pa0, pa1, pa2, pa3);
.LBB0_189:
	v_add_u32_e32 v194, s68, v221
	ds_read_b64_tr_b16 v[82:83], v194 offset:0
	ds_read_b64_tr_b16 v[84:85], v194 offset:0x800
	ds_read_b64_tr_b16 v[86:87], v194 offset:0x1000
	ds_read_b64_tr_b16 v[88:89], v194 offset:0x1800
	ds_read_b64_tr_b16 v[90:91], v194 offset:0x2000
	ds_read_b64_tr_b16 v[92:93], v194 offset:0x2800
	ds_read_b64_tr_b16 v[94:95], v194 offset:0x3000
	ds_read_b64_tr_b16 v[96:97], v194 offset:0x3800
	s_waitcnt lgkmcnt(0)
	s_nop 0
	v_mfma_f32_32x32x16_bf16 v[50:65], v[66:69], v[82:85], v[50:65]
	ds_read_b64_tr_b16 v[82:83], v194 offset:0x200
	ds_read_b64_tr_b16 v[84:85], v194 offset:0xa00
	v_mfma_f32_32x32x16_bf16 v[50:65], v[70:73], v[86:89], v[50:65]
	ds_read_b64_tr_b16 v[86:87], v194 offset:0x1200
	ds_read_b64_tr_b16 v[88:89], v194 offset:0x1a00
	v_mfma_f32_32x32x16_bf16 v[50:65], v[74:77], v[90:93], v[50:65]
	ds_read_b64_tr_b16 v[90:91], v194 offset:0x2200
	ds_read_b64_tr_b16 v[92:93], v194 offset:0x2a00
	v_mfma_f32_32x32x16_bf16 v[50:65], v[78:81], v[94:97], v[50:65]
	ds_read_b64_tr_b16 v[94:95], v194 offset:0x3200
	ds_read_b64_tr_b16 v[96:97], v194 offset:0x3a00
	s_waitcnt lgkmcnt(0)
	v_mfma_f32_32x32x16_bf16 v[34:49], v[66:69], v[82:85], v[34:49]
	ds_read_b64_tr_b16 v[82:83], v194 offset:0x400
	ds_read_b64_tr_b16 v[84:85], v194 offset:0xc00
	v_mfma_f32_32x32x16_bf16 v[34:49], v[70:73], v[86:89], v[34:49]
	ds_read_b64_tr_b16 v[86:87], v194 offset:0x1400
	ds_read_b64_tr_b16 v[88:89], v194 offset:0x1c00
	v_mfma_f32_32x32x16_bf16 v[34:49], v[74:77], v[90:93], v[34:49]
	ds_read_b64_tr_b16 v[90:91], v194 offset:0x2400
	ds_read_b64_tr_b16 v[92:93], v194 offset:0x2c00
	v_mfma_f32_32x32x16_bf16 v[34:49], v[78:81], v[94:97], v[34:49]
	ds_read_b64_tr_b16 v[94:95], v194 offset:0x3400
	ds_read_b64_tr_b16 v[96:97], v194 offset:0x3c00
	s_waitcnt lgkmcnt(0)
	v_mfma_f32_32x32x16_bf16 v[18:33], v[66:69], v[82:85], v[18:33]
	ds_read_b64_tr_b16 v[82:83], v194 offset:0x600
	ds_read_b64_tr_b16 v[84:85], v194 offset:0xe00
	v_mfma_f32_32x32x16_bf16 v[18:33], v[70:73], v[86:89], v[18:33]
	ds_read_b64_tr_b16 v[86:87], v194 offset:0x1600
	ds_read_b64_tr_b16 v[88:89], v194 offset:0x1e00
	v_mfma_f32_32x32x16_bf16 v[18:33], v[74:77], v[90:93], v[18:33]
	ds_read_b64_tr_b16 v[90:91], v194 offset:0x2600
	ds_read_b64_tr_b16 v[92:93], v194 offset:0x2e00
	v_mfma_f32_32x32x16_bf16 v[18:33], v[78:81], v[94:97], v[18:33]
	ds_read_b64_tr_b16 v[94:95], v194 offset:0x3600
	ds_read_b64_tr_b16 v[96:97], v194 offset:0x3e00
	s_waitcnt lgkmcnt(0)
	v_mfma_f32_32x32x16_bf16 v[2:17], v[66:69], v[82:85], v[2:17]
	s_cmp_gt_i32 s95, s24
	s_cselect_b64 s[58:59], -1, 0
	s_cmp_lt_i32 s15, s24
	s_cselect_b64 vcc, -1, 0
	v_mov_b32_e32 v234, s76
	v_mfma_f32_32x32x16_bf16 v[2:17], v[70:73], v[86:89], v[2:17]
	v_mfma_f32_32x32x16_bf16 v[2:17], v[74:77], v[90:93], v[2:17]
	v_mfma_f32_32x32x16_bf16 v[2:17], v[78:81], v[94:97], v[2:17]
	s_and_saveexec_b64 s[60:61], vcc
	s_cbranch_execz .LBB0_193
	s_cmp_gt_i32 s91, s25
	s_cselect_b64 vcc, -1, 0
	s_mov_b64 s[64:65], -1
	s_and_saveexec_b64 s[62:63], vcc
	s_cbranch_execz .LBB0_192
	v_add_u32_e32 v230, s77, v225
	v_add_u32_e32 v66, 0x80, v230
	v_add_u32_e32 v68, 0x81, v230
	v_add_u32_e32 v70, 0x82, v230
	v_add_u32_e32 v72, 0x83, v230
	v_med3_i32 v67, v66, s39, v198
	v_med3_i32 v66, v66, s33, v199
	v_med3_i32 v69, v68, s39, v198
	v_med3_i32 v68, v68, s33, v199
	v_med3_i32 v71, v70, s39, v198
	v_med3_i32 v70, v70, s33, v199
	v_med3_i32 v73, v72, s39, v198
	v_med3_i32 v72, v72, s33, v199
	v_lshl_add_u32 v67, v67, 2, s76
	v_lshl_add_u32 v66, v66, 2, s76
	v_lshl_add_u32 v69, v69, 2, s76
	v_lshl_add_u32 v68, v68, 2, s76
	v_lshl_add_u32 v70, v70, 2, s76
	v_lshl_add_u32 v72, v72, 2, s76
	v_lshl_add_u32 v71, v71, 2, s76
	v_lshl_add_u32 v73, v73, 2, s76
	ds_read_b32 v194, v67 offset:516
	ds_read_b32 v66, v66 offset:644
	ds_read_b32 v195, v69 offset:516
	ds_read_b32 v67, v68 offset:644
	ds_read_b32 v234, v71 offset:516
	ds_read_b32 v68, v70 offset:644
	ds_read_b32 v235, v73 offset:516
	ds_read_b32 v69, v72 offset:644
	v_add_u32_e32 v70, 0x88, v230
	v_add_u32_e32 v72, 0x89, v230
	v_add_u32_e32 v74, 0x8a, v230
	v_add_u32_e32 v76, 0x8b, v230
	v_med3_i32 v71, v70, s39, v198
	v_med3_i32 v70, v70, s33, v199
	v_med3_i32 v73, v72, s39, v198
	v_med3_i32 v72, v72, s33, v199
	v_med3_i32 v75, v74, s39, v198
	v_med3_i32 v74, v74, s33, v199
	v_med3_i32 v77, v76, s39, v198
	v_med3_i32 v76, v76, s33, v199
	v_lshl_add_u32 v71, v71, 2, s76
	v_lshl_add_u32 v70, v70, 2, s76
	v_lshl_add_u32 v73, v73, 2, s76
	v_lshl_add_u32 v72, v72, 2, s76
	v_lshl_add_u32 v74, v74, 2, s76
	v_lshl_add_u32 v76, v76, 2, s76
	v_lshl_add_u32 v75, v75, 2, s76
	v_lshl_add_u32 v77, v77, 2, s76
	ds_read_b32 v236, v71 offset:516
	ds_read_b32 v70, v70 offset:644
	ds_read_b32 v237, v73 offset:516
	ds_read_b32 v71, v72 offset:644
	ds_read_b32 v238, v75 offset:516
	ds_read_b32 v72, v74 offset:644
	ds_read_b32 v239, v77 offset:516
	ds_read_b32 v73, v76 offset:644
	v_add_u32_e32 v74, 0x90, v230
	v_add_u32_e32 v76, 0x91, v230
	v_add_u32_e32 v78, 0x92, v230
	v_add_u32_e32 v80, 0x93, v230
	v_med3_i32 v75, v74, s39, v198
	v_med3_i32 v74, v74, s33, v199
	v_med3_i32 v77, v76, s39, v198
	v_med3_i32 v76, v76, s33, v199
	v_med3_i32 v79, v78, s39, v198
	v_med3_i32 v78, v78, s33, v199
	v_med3_i32 v81, v80, s39, v198
	v_med3_i32 v80, v80, s33, v199
	v_lshl_add_u32 v75, v75, 2, s76
	v_lshl_add_u32 v74, v74, 2, s76
	v_lshl_add_u32 v77, v77, 2, s76
	v_lshl_add_u32 v76, v76, 2, s76
	v_lshl_add_u32 v78, v78, 2, s76
	v_lshl_add_u32 v80, v80, 2, s76
	v_lshl_add_u32 v79, v79, 2, s76
	v_lshl_add_u32 v81, v81, 2, s76
	ds_read_b32 v240, v75 offset:516
	ds_read_b32 v74, v74 offset:644
	ds_read_b32 v241, v77 offset:516
	ds_read_b32 v75, v76 offset:644
	ds_read_b32 v242, v79 offset:516
	ds_read_b32 v76, v78 offset:644
	ds_read_b32 v243, v81 offset:516
	ds_read_b32 v77, v80 offset:644
	v_add_u32_e32 v78, 0x98, v230
	v_add_u32_e32 v80, 0x99, v230
	v_add_u32_e32 v82, 0x9a, v230
	v_med3_i32 v79, v78, s39, v198
	v_med3_i32 v78, v78, s33, v199
	v_med3_i32 v81, v80, s39, v198
	v_med3_i32 v80, v80, s33, v199
	v_med3_i32 v83, v82, s39, v198
	v_med3_i32 v82, v82, s33, v199
	v_add_u32_e32 v84, 0x9b, v230
	s_waitcnt lgkmcnt(14)
; template <int MODE>
; __device__ __forceinline__ void partialSM(f32x16& p0, f32x16& p1, float& m_reg, float& mn, float& alpha, int relh, int relw_min, int relw_max, const float* lut) {
;     ...
;     if (nearT) {
; #pragma unroll
;       for (int r = 0; r < 16; ++r) { const int i0 = relh + (r & 3) + 8 * (r >> 2);
;         const int a0 = min(max(i0, -129), 129) + 129, a1 = min(max(i0 + 32, -129), 129) + 129;
;         p0[r] = fmaf(p0[r], C, lut[a0]); p1[r] = fmaf(p1[r], C, lut[a1]); }
;     } else {
; #pragma unroll
;       for (int r = 0; r < 16; ++r) { p0[r] = fmaf(p0[r], C, cfar); p1[r] = fmaf(p1[r], C, cfar); }
;     }
;     float pmax = p0[0];
; #pragma unroll
;     for (int r = 1; r < 16; ++r) pmax = fmaxf(pmax, p0[r]);
; #pragma unroll
;     for (int r = 0; r < 16; ++r) pmax = fmaxf(pmax, p1[r]);
;     { auto rr = __builtin_amdgcn_permlane32_swap(__float_as_uint(pmax), __float_as_uint(pmax), false, false);
;       pmax = fmaxf(__uint_as_float(rr[0]), __uint_as_float(rr[1])); }
;     if (__builtin_expect(__all(pmax - m_reg <= THR2), 1)) { mn = m_reg; alpha = 1.f; }
;     else { mn = fmaxf(m_reg, pmax); alpha = __builtin_amdgcn_exp2f(m_reg - mn); m_reg = mn; }
; #pragma unroll
;     for (int r = 0; r < 16; ++r) p0[r] = __builtin_amdgcn_exp2f(p0[r] - mn);
; #pragma unroll
;     for (int r = 0; r < 16; ++r) p1[r] = p1[r] - mn;
	v_fmac_f32_e32 v194, 0x3e38aa3b, v114
	v_fmac_f32_e32 v195, 0x3e38aa3b, v115
	v_lshl_add_u32 v79, v79, 2, s76
	v_lshl_add_u32 v78, v78, 2, s76
	v_lshl_add_u32 v81, v81, 2, s76
	v_lshl_add_u32 v80, v80, 2, s76
	v_lshl_add_u32 v82, v82, 2, s76
	v_med3_i32 v85, v84, s39, v198
	v_med3_i32 v84, v84, s33, v199
	v_fmac_f32_e32 v234, 0x3e38aa3b, v116
	v_fmac_f32_e32 v235, 0x3e38aa3b, v117
	v_lshl_add_u32 v83, v83, 2, s76
	v_lshl_add_u32 v85, v85, 2, s76
	v_lshl_add_u32 v84, v84, 2, s76
	ds_read_b32 v230, v79 offset:516
	ds_read_b32 v78, v78 offset:644
	ds_read_b32 v244, v81 offset:516
	ds_read_b32 v79, v80 offset:644
	ds_read_b32 v245, v83 offset:516
	ds_read_b32 v80, v82 offset:644
	ds_read_b32 v246, v85 offset:516
	ds_read_b32 v81, v84 offset:644
	v_max_f32_e32 v82, v194, v195
	v_fmac_f32_e32 v236, 0x3e38aa3b, v118
	s_waitcnt lgkmcnt(14)
	v_fmac_f32_e32 v237, 0x3e38aa3b, v119
	v_max3_f32 v82, v82, v234, v235
	v_fmac_f32_e32 v238, 0x3e38aa3b, v120
	v_fmac_f32_e32 v239, 0x3e38aa3b, v121
	v_max3_f32 v82, v82, v236, v237
	v_fmac_f32_e32 v240, 0x3e38aa3b, v122
	s_waitcnt lgkmcnt(13)
	v_fmac_f32_e32 v241, 0x3e38aa3b, v123
	v_max3_f32 v82, v82, v238, v239
	s_waitcnt lgkmcnt(11)
	v_fmac_f32_e32 v242, 0x3e38aa3b, v124
	s_waitcnt lgkmcnt(9)
	v_fmac_f32_e32 v243, 0x3e38aa3b, v125
	v_max3_f32 v82, v82, v240, v241
	s_waitcnt lgkmcnt(7)
	v_fmac_f32_e32 v230, 0x3e38aa3b, v126
	s_waitcnt lgkmcnt(5)
	v_fmac_f32_e32 v244, 0x3e38aa3b, v127
	v_max3_f32 v82, v82, v242, v243
	s_waitcnt lgkmcnt(3)
	v_fmac_f32_e32 v245, 0x3e38aa3b, v128
	s_waitcnt lgkmcnt(1)
	v_fmac_f32_e32 v246, 0x3e38aa3b, v129
	v_max3_f32 v82, v82, v230, v244
	v_max3_f32 v84, v82, v245, v246
	v_pk_fma_f32 v[82:83], v[98:99], s[48:49], v[66:67] op_sel_hi:[1,0,1]
	v_pk_fma_f32 v[86:87], v[102:103], s[48:49], v[70:71] op_sel_hi:[1,0,1]
	v_max3_f32 v66, v84, v82, v83
	v_pk_fma_f32 v[84:85], v[100:101], s[48:49], v[68:69] op_sel_hi:[1,0,1]
	v_pk_fma_f32 v[88:89], v[104:105], s[48:49], v[72:73] op_sel_hi:[1,0,1]
	v_max3_f32 v66, v66, v84, v85
	v_max3_f32 v66, v66, v86, v87
	v_max3_f32 v66, v66, v88, v89
	v_pk_fma_f32 v[90:91], v[106:107], s[48:49], v[74:75] op_sel_hi:[1,0,1]
	v_pk_fma_f32 v[92:93], v[108:109], s[48:49], v[76:77] op_sel_hi:[1,0,1]
	v_max3_f32 v66, v66, v90, v91
	v_max3_f32 v66, v66, v92, v93
	v_pk_fma_f32 v[94:95], v[110:111], s[48:49], v[78:79] op_sel_hi:[1,0,1]
	s_waitcnt lgkmcnt(0)
	v_pk_fma_f32 v[96:97], v[112:113], s[48:49], v[80:81] op_sel_hi:[1,0,1]
	v_max3_f32 v66, v66, v94, v95
	v_max3_f32 v66, v66, v96, v97
	v_mov_b32_e32 v67, v66
	s_nop 1
	v_permlane32_swap_b32_e32 v66, v67
	v_max_f32_e32 v66, v66, v67
	v_sub_f32_e32 v67, v66, v231
	v_cmp_ge_f32_e32 vcc, s94, v67
	v_max_f32_e32 v66, v231, v66
	v_sub_f32_e32 v67, v231, v66
	v_exp_f32_e32 v67, v67
	s_cmp_eq_u64 vcc, exec
	s_cselect_b64 vcc, -1, 0
	v_cndmask_b32_e32 v222, v66, v231, vcc
	v_cndmask_b32_e64 v228, v67, 1.0, vcc
	v_sub_f32_e32 v66, v194, v222
	v_sub_f32_e32 v67, v195, v222
	v_sub_f32_e32 v68, v234, v222
	v_sub_f32_e32 v69, v235, v222
	v_sub_f32_e32 v70, v236, v222
	v_sub_f32_e32 v71, v237, v222
	v_sub_f32_e32 v72, v238, v222
	v_sub_f32_e32 v73, v239, v222
	v_sub_f32_e32 v74, v240, v222
	v_sub_f32_e32 v75, v241, v222
	v_sub_f32_e32 v76, v242, v222
	v_sub_f32_e32 v77, v243, v222
	v_sub_f32_e32 v78, v230, v222
	v_sub_f32_e32 v79, v244, v222
	v_sub_f32_e32 v80, v245, v222
	v_sub_f32_e32 v81, v246, v222
	v_exp_f32_e32 v66, v66
	v_exp_f32_e32 v67, v67
	v_exp_f32_e32 v68, v68
	v_exp_f32_e32 v69, v69
	v_exp_f32_e32 v70, v70
	v_exp_f32_e32 v71, v71
	v_exp_f32_e32 v72, v72
	v_exp_f32_e32 v73, v73
	v_exp_f32_e32 v74, v74
	v_exp_f32_e32 v75, v75
	v_exp_f32_e32 v76, v76
	v_exp_f32_e32 v77, v77
	v_exp_f32_e32 v78, v78
	v_exp_f32_e32 v79, v79
	v_exp_f32_e32 v80, v80
	v_exp_f32_e32 v81, v81
	v_sub_f32_e32 v97, v97, v222
	v_sub_f32_e32 v96, v96, v222
	v_sub_f32_e32 v95, v95, v222
	v_sub_f32_e32 v94, v94, v222
	v_sub_f32_e32 v93, v93, v222
	v_sub_f32_e32 v92, v92, v222
	v_sub_f32_e32 v91, v91, v222
	v_sub_f32_e32 v90, v90, v222
	v_sub_f32_e32 v89, v89, v222
	v_sub_f32_e32 v88, v88, v222
	v_sub_f32_e32 v87, v87, v222
	v_sub_f32_e32 v86, v86, v222
	v_sub_f32_e32 v85, v85, v222
	v_sub_f32_e32 v84, v84, v222
	v_sub_f32_e32 v83, v83, v222
	v_sub_f32_e32 v82, v82, v222
	s_xor_b64 s[64:65], exec, -1
